# scan inner block: each step's six LDS reads issued one step earlier into three rotating register sets, all lgkmcnt waits re-derived
# baseline (speedup 1.0000x reference)
; #define LAS __attribute__((address_space(3)))
; __device__ __forceinline__ float row16_sum(float x) { x += dpp_mov<0xB1>(x); x += dpp_mov<0x4E>(x); x += dpp_mov<0x124>(x); x += dpp_mov<0x128>(x); return x; }
; __device__ __forceinline__ void scan_phase(const KAS Args& a, LAS unsigned char* lds, int i, const int tid_, const int bid, const int nblk) {
;     ...
;                 f32x4 kk4 = *(const LAS f32x4*)(sb), nb4 = *(const LAS f32x4*)(sb + 64), w4 = *(const LAS f32x4*)(sb + 128), k4 = *(const LAS f32x4*)(sb + 192), r4 = *(const LAS f32x4*)(sb + 256);
;                 float v = vb[0], ysel = 0.f;
; #pragma unroll
;                 for (int t = 0; t < TC; ++t) {
;                     f32x4 kk4n = kk4, nb4n = nb4, w4n = w4, k4n = k4, r4n = r4; float vn = v;
;                     if (t + 1 < TC) { const LAS float* sn = sb + (t + 1) * SST;
;                         kk4n = *(const LAS f32x4*)(sn); nb4n = *(const LAS f32x4*)(sn + 64); w4n = *(const LAS f32x4*)(sn + 128); k4n = *(const LAS f32x4*)(sn + 192); r4n = *(const LAS f32x4*)(sn + 256); vn = vb[(t + 1) * SST]; }
;                     __builtin_amdgcn_sched_barrier(0x6);
;                     float sa = fmaf(S[3], kk4[3], fmaf(S[2], kk4[2], fmaf(S[1], kk4[1], S[0] * kk4[0])));
;                     const f32x4 Tm = S * w4 + k4 * v;
;                     sa = row16_sum(sa);
;                     S = Tm + nb4 * sa;
;                     float y = fmaf(S[3], r4[3], fmaf(S[2], r4[2], fmaf(S[1], r4[1], S[0] * r4[0]))); y = row16_sum(y);
;                     ysel = (cgp == (t & 15)) ? y : ysel;
;                     if ((t & 15) == 15) yb[(t - 15 + cgp) * 32 + rl] = ysel;
;                     kk4 = kk4n; nb4 = nb4n; w4 = w4n; k4 = k4n; r4 = r4n; v = vn; }
.LBB0_190:
	s_and_b32 s2, s67, 1
	s_mul_i32 s3, s2, 0xb000
	s_add_i32 s3, s94, s3
	v_add_u32_e32 v124, s3, v114
	v_add_u32_e32 v110, s3, v120
	ds_read_b128 v[28:31], v124
	ds_read_b128 v[32:35], v124 offset:256
	ds_read_b128 v[40:43], v124 offset:512
	ds_read_b128 v[44:47], v124 offset:768
	ds_read_b128 v[48:51], v124 offset:1024
	ds_read_b32 v2, v110 offset:1280
	ds_read_b128 v[52:55], v124 offset:1408
	ds_read_b128 v[56:59], v124 offset:1664
	ds_read_b128 v[60:63], v124 offset:1920
	ds_read_b128 v[64:67], v124 offset:2176
	ds_read_b128 v[106:109], v124 offset:2432
	ds_read_b32 v122, v110 offset:2688
	ds_read_b128 v[188:191], v124 offset:2816
	ds_read_b128 v[192:195], v124 offset:3072
	ds_read_b128 v[196:199], v124 offset:3328
	ds_read_b128 v[200:203], v124 offset:3584
	ds_read_b128 v[204:207], v124 offset:3840
	ds_read_b32 v208, v110 offset:4096
	s_waitcnt lgkmcnt(15)
	v_mul_f32_e32 v123, v36, v28
	v_fmac_f32_e32 v123, v37, v29
	v_fmac_f32_e32 v123, v38, v30
	v_fmac_f32_e32 v123, v39, v31
	s_waitcnt lgkmcnt(12)
	v_pk_mul_f32 v[28:29], v[46:47], v[2:3] op_sel_hi:[1,0]
	v_pk_mul_f32 v[30:31], v[44:45], v[2:3] op_sel_hi:[1,0]
	v_add_f32_dpp v2, v123, v123 quad_perm:[1,0,3,2] row_mask:0xf bank_mask:0xf bound_ctrl:1
	v_pk_fma_f32 v[30:31], v[36:37], v[40:41], v[30:31]
	v_pk_fma_f32 v[28:29], v[38:39], v[42:43], v[28:29]
	v_add_f32_dpp v2, v2, v2 quad_perm:[2,3,0,1] row_mask:0xf bank_mask:0xf bound_ctrl:1
	s_lshl_b32 s2, s2, 12
	s_add_i32 s63, s64, s2
	v_add_f32_dpp v2, v2, v2 row_ror:4 row_mask:0xf bank_mask:0xf bound_ctrl:1
	s_add_i32 s62, s67, 1
	s_andn2_b64 vcc, exec, s[60:61]
	v_add_f32_dpp v2, v2, v2 row_ror:8 row_mask:0xf bank_mask:0xf bound_ctrl:1
	v_pk_fma_f32 v[126:127], v[32:33], v[2:3], v[30:31] op_sel_hi:[1,0,1]
	v_pk_fma_f32 v[128:129], v[34:35], v[2:3], v[28:29] op_sel_hi:[1,0,1]
	s_waitcnt lgkmcnt(11)
	v_mul_f32_e32 v52, v52, v126
	v_fmac_f32_e32 v52, v127, v53
	v_mul_f32_e32 v2, v48, v126
	v_fmac_f32_e32 v52, v128, v54
	v_fmac_f32_e32 v2, v127, v49
	v_fmac_f32_e32 v52, v129, v55
	v_fmac_f32_e32 v2, v128, v50
	v_fmac_f32_e32 v2, v129, v51
	v_add_f32_dpp v52, v52, v52 quad_perm:[1,0,3,2] row_mask:0xf bank_mask:0xf bound_ctrl:1
	s_waitcnt lgkmcnt(9)
	v_pk_mul_f32 v[48:49], v[60:61], v[126:127]
	v_add_f32_dpp v2, v2, v2 quad_perm:[1,0,3,2] row_mask:0xf bank_mask:0xf bound_ctrl:1
	v_add_f32_dpp v52, v52, v52 quad_perm:[2,3,0,1] row_mask:0xf bank_mask:0xf bound_ctrl:1
	v_pk_mul_f32 v[50:51], v[62:63], v[128:129]
	v_add_f32_dpp v2, v2, v2 quad_perm:[2,3,0,1] row_mask:0xf bank_mask:0xf bound_ctrl:1
	v_add_f32_dpp v52, v52, v52 row_ror:4 row_mask:0xf bank_mask:0xf bound_ctrl:1
	s_waitcnt lgkmcnt(6)
	v_pk_fma_f32 v[48:49], v[64:65], v[122:123], v[48:49] op_sel_hi:[1,0,1]
	v_add_f32_dpp v2, v2, v2 row_ror:4 row_mask:0xf bank_mask:0xf bound_ctrl:1
	v_add_f32_dpp v52, v52, v52 row_ror:8 row_mask:0xf bank_mask:0xf bound_ctrl:1
	v_pk_fma_f32 v[50:51], v[66:67], v[122:123], v[50:51] op_sel_hi:[1,0,1]
	v_pk_fma_f32 v[122:123], v[56:57], v[52:53], v[48:49] op_sel_hi:[1,0,1]
	v_add_f32_dpp v2, v2, v2 row_ror:8 row_mask:0xf bank_mask:0xf bound_ctrl:1
	v_mul_f32_e32 v48, v106, v122
	v_cndmask_b32_e64 v125, 0, v2, s[8:9]
	ds_read_b128 v[136:139], v124 offset:4224
	ds_read_b128 v[140:143], v124 offset:4480
	ds_read_b128 v[144:147], v124 offset:4736
	ds_read_b128 v[148:151], v124 offset:4992
	ds_read_b128 v[152:155], v124 offset:5248
	ds_read_b32 v156, v110 offset:5504
	v_pk_fma_f32 v[126:127], v[58:59], v[52:53], v[50:51] op_sel_hi:[1,0,1]
	v_fmac_f32_e32 v48, v123, v107
	v_fmac_f32_e32 v48, v126, v108
	s_waitcnt lgkmcnt(11)
	v_mul_f32_e32 v108, v188, v122
	v_fmac_f32_e32 v108, v123, v189
	v_fmac_f32_e32 v108, v126, v190
	v_fmac_f32_e32 v108, v127, v191
	s_waitcnt lgkmcnt(9)
	v_pk_mul_f32 v[28:29], v[196:197], v[122:123]
	v_pk_mul_f32 v[30:31], v[198:199], v[126:127]
	s_waitcnt lgkmcnt(6)
	v_pk_fma_f32 v[28:29], v[200:201], v[208:209], v[28:29] op_sel_hi:[1,0,1]
	v_pk_fma_f32 v[30:31], v[202:203], v[208:209], v[30:31] op_sel_hi:[1,0,1]
	v_add_f32_dpp v2, v108, v108 quad_perm:[1,0,3,2] row_mask:0xf bank_mask:0xf bound_ctrl:1
	v_fmac_f32_e32 v48, v127, v109
	s_nop 0
	v_add_f32_dpp v2, v2, v2 quad_perm:[2,3,0,1] row_mask:0xf bank_mask:0xf bound_ctrl:1
	v_add_f32_dpp v48, v48, v48 quad_perm:[1,0,3,2] row_mask:0xf bank_mask:0xf bound_ctrl:1
	s_nop 0
	v_add_f32_dpp v2, v2, v2 row_ror:4 row_mask:0xf bank_mask:0xf bound_ctrl:1
	v_add_f32_dpp v48, v48, v48 quad_perm:[2,3,0,1] row_mask:0xf bank_mask:0xf bound_ctrl:1
	s_nop 0
	v_add_f32_dpp v2, v2, v2 row_ror:8 row_mask:0xf bank_mask:0xf bound_ctrl:1
	v_pk_fma_f32 v[108:109], v[192:193], v[2:3], v[28:29] op_sel_hi:[1,0,1]
	v_pk_fma_f32 v[122:123], v[194:195], v[2:3], v[30:31] op_sel_hi:[1,0,1]
	v_mul_f32_e32 v2, v204, v108
	v_fmac_f32_e32 v2, v109, v205
	v_fmac_f32_e32 v2, v122, v206
	v_fmac_f32_e32 v2, v123, v207
	v_add_f32_dpp v48, v48, v48 row_ror:4 row_mask:0xf bank_mask:0xf bound_ctrl:1
	s_nop 0
	v_add_f32_dpp v2, v2, v2 quad_perm:[1,0,3,2] row_mask:0xf bank_mask:0xf bound_ctrl:1
	v_add_f32_dpp v48, v48, v48 row_ror:8 row_mask:0xf bank_mask:0xf bound_ctrl:1
	v_cndmask_b32_e64 v107, v125, v48, s[10:11]
	v_add_f32_dpp v2, v2, v2 quad_perm:[2,3,0,1] row_mask:0xf bank_mask:0xf bound_ctrl:1
	ds_read_b128 v[160:163], v124 offset:5632
	ds_read_b128 v[164:167], v124 offset:5888
	ds_read_b128 v[168:171], v124 offset:6144
	ds_read_b128 v[172:175], v124 offset:6400
	ds_read_b128 v[176:179], v124 offset:6656
	ds_read_b32 v158, v110 offset:6912
	v_add_f32_dpp v2, v2, v2 row_ror:4 row_mask:0xf bank_mask:0xf bound_ctrl:1
	s_nop 1
	v_add_f32_dpp v2, v2, v2 row_ror:8 row_mask:0xf bank_mask:0xf bound_ctrl:1
	v_cndmask_b32_e64 v125, v107, v2, s[12:13]
	s_waitcnt lgkmcnt(11)
; #define LAS __attribute__((address_space(3)))
; __device__ __forceinline__ float row16_sum(float x) { x += dpp_mov<0xB1>(x); x += dpp_mov<0x4E>(x); x += dpp_mov<0x124>(x); x += dpp_mov<0x128>(x); return x; }
; __device__ __forceinline__ void scan_phase(const KAS Args& a, LAS unsigned char* lds, int i, const int tid_, const int bid, const int nblk) {
;     ...
;                 f32x4 kk4 = *(const LAS f32x4*)(sb), nb4 = *(const LAS f32x4*)(sb + 64), w4 = *(const LAS f32x4*)(sb + 128), k4 = *(const LAS f32x4*)(sb + 192), r4 = *(const LAS f32x4*)(sb + 256);
;                 float v = vb[0], ysel = 0.f;
; #pragma unroll
;                 for (int t = 0; t < TC; ++t) {
;                     f32x4 kk4n = kk4, nb4n = nb4, w4n = w4, k4n = k4, r4n = r4; float vn = v;
;                     if (t + 1 < TC) { const LAS float* sn = sb + (t + 1) * SST;
;                         kk4n = *(const LAS f32x4*)(sn); nb4n = *(const LAS f32x4*)(sn + 64); w4n = *(const LAS f32x4*)(sn + 128); k4n = *(const LAS f32x4*)(sn + 192); r4n = *(const LAS f32x4*)(sn + 256); vn = vb[(t + 1) * SST]; }
;                     __builtin_amdgcn_sched_barrier(0x6);
;                     float sa = fmaf(S[3], kk4[3], fmaf(S[2], kk4[2], fmaf(S[1], kk4[1], S[0] * kk4[0])));
;                     const f32x4 Tm = S * w4 + k4 * v;
;                     sa = row16_sum(sa);
;                     S = Tm + nb4 * sa;
;                     float y = fmaf(S[3], r4[3], fmaf(S[2], r4[2], fmaf(S[1], r4[1], S[0] * r4[0]))); y = row16_sum(y);
;                     ysel = (cgp == (t & 15)) ? y : ysel;
;                     if ((t & 15) == 15) yb[(t - 15 + cgp) * 32 + rl] = ysel;
;                     kk4 = kk4n; nb4 = nb4n; w4 = w4n; k4 = k4n; r4 = r4n; v = vn; }
	v_mul_f32_e32 v107, v136, v108
	v_fmac_f32_e32 v107, v109, v137
	v_fmac_f32_e32 v107, v122, v138
	v_fmac_f32_e32 v107, v123, v139
	s_waitcnt lgkmcnt(9)
	v_pk_mul_f32 v[48:49], v[144:145], v[108:109]
	v_pk_mul_f32 v[50:51], v[146:147], v[122:123]
	v_add_f32_dpp v56, v107, v107 quad_perm:[1,0,3,2] row_mask:0xf bank_mask:0xf bound_ctrl:1
	s_waitcnt lgkmcnt(6)
	v_pk_fma_f32 v[48:49], v[148:149], v[156:157], v[48:49] op_sel_hi:[1,0,1]
	v_pk_fma_f32 v[50:51], v[150:151], v[156:157], v[50:51] op_sel_hi:[1,0,1]
	v_add_f32_dpp v56, v56, v56 quad_perm:[2,3,0,1] row_mask:0xf bank_mask:0xf bound_ctrl:1
	ds_read_b128 v[188:191], v124 offset:7040
	ds_read_b128 v[192:195], v124 offset:7296
	ds_read_b128 v[196:199], v124 offset:7552
	ds_read_b128 v[200:203], v124 offset:7808
	ds_read_b128 v[204:207], v124 offset:8064
	ds_read_b32 v208, v110 offset:8320
	v_add_f32_dpp v56, v56, v56 row_ror:4 row_mask:0xf bank_mask:0xf bound_ctrl:1
	s_nop 1
	v_add_f32_dpp v56, v56, v56 row_ror:8 row_mask:0xf bank_mask:0xf bound_ctrl:1
	v_pk_fma_f32 v[106:107], v[140:141], v[56:57], v[48:49] op_sel_hi:[1,0,1]
	v_pk_fma_f32 v[108:109], v[142:143], v[56:57], v[50:51] op_sel_hi:[1,0,1]
	v_mul_f32_e32 v48, v152, v106
	v_fmac_f32_e32 v48, v107, v153
	v_fmac_f32_e32 v48, v108, v154
	v_fmac_f32_e32 v48, v109, v155
	s_nop 1
	v_add_f32_dpp v48, v48, v48 quad_perm:[1,0,3,2] row_mask:0xf bank_mask:0xf bound_ctrl:1
	s_nop 1
	v_add_f32_dpp v48, v48, v48 quad_perm:[2,3,0,1] row_mask:0xf bank_mask:0xf bound_ctrl:1
	s_nop 1
	v_add_f32_dpp v48, v48, v48 row_ror:4 row_mask:0xf bank_mask:0xf bound_ctrl:1
	s_nop 1
	v_add_f32_dpp v48, v48, v48 row_ror:8 row_mask:0xf bank_mask:0xf bound_ctrl:1
	v_cndmask_b32_e64 v123, v125, v48, s[14:15]
	s_waitcnt lgkmcnt(11)
	v_mul_f32_e32 v125, v160, v106
	v_fmac_f32_e32 v125, v107, v161
	v_fmac_f32_e32 v125, v108, v162
	v_fmac_f32_e32 v125, v109, v163
	s_waitcnt lgkmcnt(9)
	v_pk_mul_f32 v[28:29], v[168:169], v[106:107]
	v_pk_mul_f32 v[30:31], v[170:171], v[108:109]
	s_waitcnt lgkmcnt(6)
	v_pk_fma_f32 v[28:29], v[172:173], v[158:159], v[28:29] op_sel_hi:[1,0,1]
	v_pk_fma_f32 v[30:31], v[174:175], v[158:159], v[30:31] op_sel_hi:[1,0,1]
	v_add_f32_dpp v2, v125, v125 quad_perm:[1,0,3,2] row_mask:0xf bank_mask:0xf bound_ctrl:1
	ds_read_b128 v[136:139], v124 offset:8448
	ds_read_b128 v[140:143], v124 offset:8704
	ds_read_b128 v[144:147], v124 offset:8960
	ds_read_b128 v[148:151], v124 offset:9216
	ds_read_b128 v[152:155], v124 offset:9472
	ds_read_b32 v156, v110 offset:9728
	v_add_f32_dpp v2, v2, v2 quad_perm:[2,3,0,1] row_mask:0xf bank_mask:0xf bound_ctrl:1
	s_nop 1
	v_add_f32_dpp v2, v2, v2 row_ror:4 row_mask:0xf bank_mask:0xf bound_ctrl:1
	s_nop 1
	v_add_f32_dpp v2, v2, v2 row_ror:8 row_mask:0xf bank_mask:0xf bound_ctrl:1
	v_pk_fma_f32 v[106:107], v[164:165], v[2:3], v[28:29] op_sel_hi:[1,0,1]
	v_pk_fma_f32 v[108:109], v[166:167], v[2:3], v[30:31] op_sel_hi:[1,0,1]
	v_mul_f32_e32 v2, v176, v106
	v_fmac_f32_e32 v2, v107, v177
	v_fmac_f32_e32 v2, v108, v178
	s_waitcnt lgkmcnt(11)
	v_mul_f32_e32 v125, v188, v106
	v_fmac_f32_e32 v2, v109, v179
	v_fmac_f32_e32 v125, v107, v189
	v_fmac_f32_e32 v125, v108, v190
	v_add_f32_dpp v2, v2, v2 quad_perm:[1,0,3,2] row_mask:0xf bank_mask:0xf bound_ctrl:1
	v_fmac_f32_e32 v125, v109, v191
	s_waitcnt lgkmcnt(9)
	v_pk_mul_f32 v[48:49], v[196:197], v[106:107]
	v_add_f32_dpp v2, v2, v2 quad_perm:[2,3,0,1] row_mask:0xf bank_mask:0xf bound_ctrl:1
	v_add_f32_dpp v56, v125, v125 quad_perm:[1,0,3,2] row_mask:0xf bank_mask:0xf bound_ctrl:1
	v_pk_mul_f32 v[50:51], v[198:199], v[108:109]
	v_add_f32_dpp v2, v2, v2 row_ror:4 row_mask:0xf bank_mask:0xf bound_ctrl:1
	v_add_f32_dpp v56, v56, v56 quad_perm:[2,3,0,1] row_mask:0xf bank_mask:0xf bound_ctrl:1
	s_nop 0
	v_add_f32_dpp v2, v2, v2 row_ror:8 row_mask:0xf bank_mask:0xf bound_ctrl:1
	v_cndmask_b32_e64 v123, v123, v2, s[16:17]
	v_add_f32_dpp v56, v56, v56 row_ror:4 row_mask:0xf bank_mask:0xf bound_ctrl:1
	s_waitcnt lgkmcnt(6)
	v_pk_fma_f32 v[48:49], v[200:201], v[208:209], v[48:49] op_sel_hi:[1,0,1]
	ds_read_b128 v[160:163], v124 offset:9856
	ds_read_b128 v[164:167], v124 offset:10112
	ds_read_b128 v[168:171], v124 offset:10368
	ds_read_b128 v[172:175], v124 offset:10624
	ds_read_b128 v[176:179], v124 offset:10880
	ds_read_b32 v158, v110 offset:11136
	v_add_f32_dpp v56, v56, v56 row_ror:8 row_mask:0xf bank_mask:0xf bound_ctrl:1
	v_pk_fma_f32 v[106:107], v[192:193], v[56:57], v[48:49] op_sel_hi:[1,0,1]
	v_pk_fma_f32 v[50:51], v[202:203], v[208:209], v[50:51] op_sel_hi:[1,0,1]
	s_waitcnt lgkmcnt(11)
	v_mul_f32_e32 v125, v136, v106
	v_pk_fma_f32 v[108:109], v[194:195], v[56:57], v[50:51] op_sel_hi:[1,0,1]
	v_fmac_f32_e32 v125, v107, v137
	v_fmac_f32_e32 v125, v108, v138
	v_mul_f32_e32 v48, v204, v106
	v_fmac_f32_e32 v125, v109, v139
	s_waitcnt lgkmcnt(9)
	v_pk_mul_f32 v[28:29], v[144:145], v[106:107]
	v_pk_mul_f32 v[30:31], v[146:147], v[108:109]
	v_fmac_f32_e32 v48, v107, v205
	s_waitcnt lgkmcnt(6)
; #define LAS __attribute__((address_space(3)))
; __device__ __forceinline__ float row16_sum(float x) { x += dpp_mov<0xB1>(x); x += dpp_mov<0x4E>(x); x += dpp_mov<0x124>(x); x += dpp_mov<0x128>(x); return x; }
; __device__ __forceinline__ void scan_phase(const KAS Args& a, LAS unsigned char* lds, int i, const int tid_, const int bid, const int nblk) {
;     ...
;                 f32x4 kk4 = *(const LAS f32x4*)(sb), nb4 = *(const LAS f32x4*)(sb + 64), w4 = *(const LAS f32x4*)(sb + 128), k4 = *(const LAS f32x4*)(sb + 192), r4 = *(const LAS f32x4*)(sb + 256);
;                 float v = vb[0], ysel = 0.f;
; #pragma unroll
;                 for (int t = 0; t < TC; ++t) {
;                     f32x4 kk4n = kk4, nb4n = nb4, w4n = w4, k4n = k4, r4n = r4; float vn = v;
;                     if (t + 1 < TC) { const LAS float* sn = sb + (t + 1) * SST;
;                         kk4n = *(const LAS f32x4*)(sn); nb4n = *(const LAS f32x4*)(sn + 64); w4n = *(const LAS f32x4*)(sn + 128); k4n = *(const LAS f32x4*)(sn + 192); r4n = *(const LAS f32x4*)(sn + 256); vn = vb[(t + 1) * SST]; }
;                     __builtin_amdgcn_sched_barrier(0x6);
;                     float sa = fmaf(S[3], kk4[3], fmaf(S[2], kk4[2], fmaf(S[1], kk4[1], S[0] * kk4[0])));
;                     const f32x4 Tm = S * w4 + k4 * v;
;                     sa = row16_sum(sa);
;                     S = Tm + nb4 * sa;
;                     float y = fmaf(S[3], r4[3], fmaf(S[2], r4[2], fmaf(S[1], r4[1], S[0] * r4[0]))); y = row16_sum(y);
;                     ysel = (cgp == (t & 15)) ? y : ysel;
;                     if ((t & 15) == 15) yb[(t - 15 + cgp) * 32 + rl] = ysel;
;                     kk4 = kk4n; nb4 = nb4n; w4 = w4n; k4 = k4n; r4 = r4n; v = vn; }
	v_pk_fma_f32 v[30:31], v[150:151], v[156:157], v[30:31] op_sel_hi:[1,0,1]
	v_pk_fma_f32 v[28:29], v[148:149], v[156:157], v[28:29] op_sel_hi:[1,0,1]
	v_add_f32_dpp v2, v125, v125 quad_perm:[1,0,3,2] row_mask:0xf bank_mask:0xf bound_ctrl:1
	v_fmac_f32_e32 v48, v108, v206
	v_fmac_f32_e32 v48, v109, v207
	v_add_f32_dpp v2, v2, v2 quad_perm:[2,3,0,1] row_mask:0xf bank_mask:0xf bound_ctrl:1
	s_nop 0
	v_add_f32_dpp v48, v48, v48 quad_perm:[1,0,3,2] row_mask:0xf bank_mask:0xf bound_ctrl:1
	v_add_f32_dpp v2, v2, v2 row_ror:4 row_mask:0xf bank_mask:0xf bound_ctrl:1
	s_nop 0
	v_add_f32_dpp v48, v48, v48 quad_perm:[2,3,0,1] row_mask:0xf bank_mask:0xf bound_ctrl:1
	v_add_f32_dpp v2, v2, v2 row_ror:8 row_mask:0xf bank_mask:0xf bound_ctrl:1
	v_pk_fma_f32 v[106:107], v[140:141], v[2:3], v[28:29] op_sel_hi:[1,0,1]
	v_add_f32_dpp v48, v48, v48 row_ror:4 row_mask:0xf bank_mask:0xf bound_ctrl:1
	v_pk_fma_f32 v[108:109], v[142:143], v[2:3], v[30:31] op_sel_hi:[1,0,1]
	v_mul_f32_e32 v2, v152, v106
	v_add_f32_dpp v48, v48, v48 row_ror:8 row_mask:0xf bank_mask:0xf bound_ctrl:1
	v_fmac_f32_e32 v2, v107, v153
	v_cndmask_b32_e64 v123, v123, v48, s[18:19]
	ds_read_b128 v[188:191], v124 offset:11264
	ds_read_b128 v[192:195], v124 offset:11520
	ds_read_b128 v[196:199], v124 offset:11776
	ds_read_b128 v[200:203], v124 offset:12032
	ds_read_b128 v[204:207], v124 offset:12288
	ds_read_b32 v208, v110 offset:12544
	v_fmac_f32_e32 v2, v108, v154
	s_waitcnt lgkmcnt(11)
	v_mul_f32_e32 v125, v160, v106
	v_fmac_f32_e32 v2, v109, v155
	v_fmac_f32_e32 v125, v107, v161
	v_fmac_f32_e32 v125, v108, v162
	v_add_f32_dpp v2, v2, v2 quad_perm:[1,0,3,2] row_mask:0xf bank_mask:0xf bound_ctrl:1
	v_fmac_f32_e32 v125, v109, v163
	s_waitcnt lgkmcnt(9)
	v_pk_mul_f32 v[48:49], v[168:169], v[106:107]
	v_add_f32_dpp v2, v2, v2 quad_perm:[2,3,0,1] row_mask:0xf bank_mask:0xf bound_ctrl:1
	v_add_f32_dpp v56, v125, v125 quad_perm:[1,0,3,2] row_mask:0xf bank_mask:0xf bound_ctrl:1
	v_pk_mul_f32 v[50:51], v[170:171], v[108:109]
	v_add_f32_dpp v2, v2, v2 row_ror:4 row_mask:0xf bank_mask:0xf bound_ctrl:1
	v_add_f32_dpp v56, v56, v56 quad_perm:[2,3,0,1] row_mask:0xf bank_mask:0xf bound_ctrl:1
	s_nop 0
	v_add_f32_dpp v2, v2, v2 row_ror:8 row_mask:0xf bank_mask:0xf bound_ctrl:1
	v_cndmask_b32_e64 v123, v123, v2, s[20:21]
	v_add_f32_dpp v56, v56, v56 row_ror:4 row_mask:0xf bank_mask:0xf bound_ctrl:1
	s_waitcnt lgkmcnt(6)
	v_pk_fma_f32 v[48:49], v[172:173], v[158:159], v[48:49] op_sel_hi:[1,0,1]
	ds_read_b128 v[136:139], v124 offset:12672
	ds_read_b128 v[140:143], v124 offset:12928
	ds_read_b128 v[144:147], v124 offset:13184
	ds_read_b128 v[148:151], v124 offset:13440
	ds_read_b128 v[152:155], v124 offset:13696
	ds_read_b32 v156, v110 offset:13952
	v_add_f32_dpp v56, v56, v56 row_ror:8 row_mask:0xf bank_mask:0xf bound_ctrl:1
	v_pk_fma_f32 v[106:107], v[164:165], v[56:57], v[48:49] op_sel_hi:[1,0,1]
	v_pk_fma_f32 v[50:51], v[174:175], v[158:159], v[50:51] op_sel_hi:[1,0,1]
	s_waitcnt lgkmcnt(11)
	v_mul_f32_e32 v125, v188, v106
	v_pk_fma_f32 v[108:109], v[166:167], v[56:57], v[50:51] op_sel_hi:[1,0,1]
	v_fmac_f32_e32 v125, v107, v189
	v_fmac_f32_e32 v125, v108, v190
	v_mul_f32_e32 v48, v176, v106
	v_fmac_f32_e32 v125, v109, v191
	s_waitcnt lgkmcnt(9)
	v_pk_mul_f32 v[28:29], v[196:197], v[106:107]
	v_pk_mul_f32 v[30:31], v[198:199], v[108:109]
	v_fmac_f32_e32 v48, v107, v177
	s_waitcnt lgkmcnt(6)
	v_pk_fma_f32 v[30:31], v[202:203], v[208:209], v[30:31] op_sel_hi:[1,0,1]
	v_pk_fma_f32 v[28:29], v[200:201], v[208:209], v[28:29] op_sel_hi:[1,0,1]
	v_add_f32_dpp v2, v125, v125 quad_perm:[1,0,3,2] row_mask:0xf bank_mask:0xf bound_ctrl:1
	v_fmac_f32_e32 v48, v108, v178
	v_fmac_f32_e32 v48, v109, v179
	v_add_f32_dpp v2, v2, v2 quad_perm:[2,3,0,1] row_mask:0xf bank_mask:0xf bound_ctrl:1
	s_nop 0
	v_add_f32_dpp v48, v48, v48 quad_perm:[1,0,3,2] row_mask:0xf bank_mask:0xf bound_ctrl:1
	v_add_f32_dpp v2, v2, v2 row_ror:4 row_mask:0xf bank_mask:0xf bound_ctrl:1
	s_nop 0
	v_add_f32_dpp v48, v48, v48 quad_perm:[2,3,0,1] row_mask:0xf bank_mask:0xf bound_ctrl:1
	v_add_f32_dpp v2, v2, v2 row_ror:8 row_mask:0xf bank_mask:0xf bound_ctrl:1
	v_pk_fma_f32 v[106:107], v[192:193], v[2:3], v[28:29] op_sel_hi:[1,0,1]
	v_add_f32_dpp v48, v48, v48 row_ror:4 row_mask:0xf bank_mask:0xf bound_ctrl:1
	v_pk_fma_f32 v[108:109], v[194:195], v[2:3], v[30:31] op_sel_hi:[1,0,1]
	v_mul_f32_e32 v2, v204, v106
	v_add_f32_dpp v48, v48, v48 row_ror:8 row_mask:0xf bank_mask:0xf bound_ctrl:1
	v_fmac_f32_e32 v2, v107, v205
	v_cndmask_b32_e64 v123, v123, v48, s[22:23]
	ds_read_b128 v[160:163], v124 offset:14080
	ds_read_b128 v[164:167], v124 offset:14336
	ds_read_b128 v[168:171], v124 offset:14592
	ds_read_b128 v[172:175], v124 offset:14848
	ds_read_b128 v[176:179], v124 offset:15104
	ds_read_b32 v158, v110 offset:15360
	v_fmac_f32_e32 v2, v108, v206
	s_waitcnt lgkmcnt(11)
	v_mul_f32_e32 v125, v136, v106
	v_fmac_f32_e32 v2, v109, v207
	v_fmac_f32_e32 v125, v107, v137
	v_fmac_f32_e32 v125, v108, v138
	v_add_f32_dpp v2, v2, v2 quad_perm:[1,0,3,2] row_mask:0xf bank_mask:0xf bound_ctrl:1
	v_fmac_f32_e32 v125, v109, v139
	s_waitcnt lgkmcnt(9)
	v_pk_mul_f32 v[48:49], v[144:145], v[106:107]
	v_add_f32_dpp v2, v2, v2 quad_perm:[2,3,0,1] row_mask:0xf bank_mask:0xf bound_ctrl:1
	v_add_f32_dpp v56, v125, v125 quad_perm:[1,0,3,2] row_mask:0xf bank_mask:0xf bound_ctrl:1
	v_pk_mul_f32 v[50:51], v[146:147], v[108:109]
	v_add_f32_dpp v2, v2, v2 row_ror:4 row_mask:0xf bank_mask:0xf bound_ctrl:1
	v_add_f32_dpp v56, v56, v56 quad_perm:[2,3,0,1] row_mask:0xf bank_mask:0xf bound_ctrl:1
	s_nop 0
	v_add_f32_dpp v2, v2, v2 row_ror:8 row_mask:0xf bank_mask:0xf bound_ctrl:1
	v_cndmask_b32_e64 v123, v123, v2, s[24:25]
	v_add_f32_dpp v56, v56, v56 row_ror:4 row_mask:0xf bank_mask:0xf bound_ctrl:1
	s_waitcnt lgkmcnt(6)
; #define LAS __attribute__((address_space(3)))
; __device__ __forceinline__ float row16_sum(float x) { x += dpp_mov<0xB1>(x); x += dpp_mov<0x4E>(x); x += dpp_mov<0x124>(x); x += dpp_mov<0x128>(x); return x; }
; __device__ __forceinline__ void scan_phase(const KAS Args& a, LAS unsigned char* lds, int i, const int tid_, const int bid, const int nblk) {
;     ...
;                 const LAS float* sb = buf + 4 * cgp; const LAS float* vb = buf + 320 + rl;
;                 f32x4 kk4 = *(const LAS f32x4*)(sb), nb4 = *(const LAS f32x4*)(sb + 64), w4 = *(const LAS f32x4*)(sb + 128), k4 = *(const LAS f32x4*)(sb + 192), r4 = *(const LAS f32x4*)(sb + 256);
;                 float v = vb[0], ysel = 0.f;
; #pragma unroll
;                 for (int t = 0; t < TC; ++t) {
;                     f32x4 kk4n = kk4, nb4n = nb4, w4n = w4, k4n = k4, r4n = r4; float vn = v;
;                     if (t + 1 < TC) { const LAS float* sn = sb + (t + 1) * SST;
;                         kk4n = *(const LAS f32x4*)(sn); nb4n = *(const LAS f32x4*)(sn + 64); w4n = *(const LAS f32x4*)(sn + 128); k4n = *(const LAS f32x4*)(sn + 192); r4n = *(const LAS f32x4*)(sn + 256); vn = vb[(t + 1) * SST]; }
;                     __builtin_amdgcn_sched_barrier(0x6);
;                     float sa = fmaf(S[3], kk4[3], fmaf(S[2], kk4[2], fmaf(S[1], kk4[1], S[0] * kk4[0])));
;                     const f32x4 Tm = S * w4 + k4 * v;
;                     sa = row16_sum(sa);
;                     S = Tm + nb4 * sa;
;                     float y = fmaf(S[3], r4[3], fmaf(S[2], r4[2], fmaf(S[1], r4[1], S[0] * r4[0]))); y = row16_sum(y);
;                     ysel = (cgp == (t & 15)) ? y : ysel;
;                     if ((t & 15) == 15) yb[(t - 15 + cgp) * 32 + rl] = ysel;
;                     kk4 = kk4n; nb4 = nb4n; w4 = w4n; k4 = k4n; r4 = r4n; v = vn; }
	v_pk_fma_f32 v[48:49], v[148:149], v[156:157], v[48:49] op_sel_hi:[1,0,1]
	ds_read_b128 v[188:191], v124 offset:15488
	ds_read_b128 v[192:195], v124 offset:15744
	ds_read_b128 v[196:199], v124 offset:16000
	ds_read_b128 v[200:203], v124 offset:16256
	ds_read_b128 v[204:207], v124 offset:16512
	ds_read_b32 v208, v110 offset:16768
	v_add_f32_dpp v56, v56, v56 row_ror:8 row_mask:0xf bank_mask:0xf bound_ctrl:1
	v_pk_fma_f32 v[50:51], v[150:151], v[156:157], v[50:51] op_sel_hi:[1,0,1]
	v_pk_fma_f32 v[52:53], v[140:141], v[56:57], v[48:49] op_sel_hi:[1,0,1]
	v_pk_fma_f32 v[54:55], v[142:143], v[56:57], v[50:51] op_sel_hi:[1,0,1]
	s_waitcnt lgkmcnt(11)
	v_mul_f32_e32 v57, v160, v52
	v_fmac_f32_e32 v57, v53, v161
	v_mul_f32_e32 v48, v152, v52
	v_fmac_f32_e32 v57, v54, v162
	v_fmac_f32_e32 v48, v53, v153
	v_fmac_f32_e32 v57, v55, v163
	s_waitcnt lgkmcnt(9)
	v_pk_mul_f32 v[28:29], v[168:169], v[52:53]
	v_pk_mul_f32 v[30:31], v[170:171], v[54:55]
	v_fmac_f32_e32 v48, v54, v154
	s_waitcnt lgkmcnt(6)
	v_pk_fma_f32 v[30:31], v[174:175], v[158:159], v[30:31] op_sel_hi:[1,0,1]
	v_pk_fma_f32 v[28:29], v[172:173], v[158:159], v[28:29] op_sel_hi:[1,0,1]
	v_add_f32_dpp v2, v57, v57 quad_perm:[1,0,3,2] row_mask:0xf bank_mask:0xf bound_ctrl:1
	v_fmac_f32_e32 v48, v55, v155
	s_nop 0
	v_add_f32_dpp v2, v2, v2 quad_perm:[2,3,0,1] row_mask:0xf bank_mask:0xf bound_ctrl:1
	v_add_f32_dpp v48, v48, v48 quad_perm:[1,0,3,2] row_mask:0xf bank_mask:0xf bound_ctrl:1
	s_nop 0
	v_add_f32_dpp v2, v2, v2 row_ror:4 row_mask:0xf bank_mask:0xf bound_ctrl:1
	v_add_f32_dpp v48, v48, v48 quad_perm:[2,3,0,1] row_mask:0xf bank_mask:0xf bound_ctrl:1
	s_nop 0
	v_add_f32_dpp v2, v2, v2 row_ror:8 row_mask:0xf bank_mask:0xf bound_ctrl:1
	v_add_f32_dpp v48, v48, v48 row_ror:4 row_mask:0xf bank_mask:0xf bound_ctrl:1
	v_pk_fma_f32 v[32:33], v[164:165], v[2:3], v[28:29] op_sel_hi:[1,0,1]
	v_pk_fma_f32 v[34:35], v[166:167], v[2:3], v[30:31] op_sel_hi:[1,0,1]
	v_add_f32_dpp v48, v48, v48 row_ror:8 row_mask:0xf bank_mask:0xf bound_ctrl:1
	v_mul_f32_e32 v2, v176, v32
	v_cndmask_b32_e64 v56, v123, v48, s[26:27]
	ds_read_b128 v[136:139], v124 offset:16896
	ds_read_b128 v[140:143], v124 offset:17152
	ds_read_b128 v[144:147], v124 offset:17408
	ds_read_b128 v[148:151], v124 offset:17664
	ds_read_b128 v[152:155], v124 offset:17920
	ds_read_b32 v156, v110 offset:18176
	v_fmac_f32_e32 v2, v33, v177
	s_waitcnt lgkmcnt(11)
	v_mul_f32_e32 v40, v188, v32
	v_fmac_f32_e32 v2, v34, v178
	v_fmac_f32_e32 v40, v33, v189
	v_fmac_f32_e32 v2, v35, v179
	v_fmac_f32_e32 v40, v34, v190
	v_fmac_f32_e32 v40, v35, v191
	v_add_f32_dpp v2, v2, v2 quad_perm:[1,0,3,2] row_mask:0xf bank_mask:0xf bound_ctrl:1
	s_waitcnt lgkmcnt(9)
	v_pk_mul_f32 v[32:33], v[196:197], v[32:33]
	v_add_f32_dpp v40, v40, v40 quad_perm:[1,0,3,2] row_mask:0xf bank_mask:0xf bound_ctrl:1
	v_add_f32_dpp v2, v2, v2 quad_perm:[2,3,0,1] row_mask:0xf bank_mask:0xf bound_ctrl:1
	s_waitcnt lgkmcnt(6)
	v_pk_fma_f32 v[32:33], v[200:201], v[208:209], v[32:33] op_sel_hi:[1,0,1]
	v_add_f32_dpp v40, v40, v40 quad_perm:[2,3,0,1] row_mask:0xf bank_mask:0xf bound_ctrl:1
	v_add_f32_dpp v2, v2, v2 row_ror:4 row_mask:0xf bank_mask:0xf bound_ctrl:1
	v_pk_mul_f32 v[34:35], v[198:199], v[34:35]
	v_add_f32_dpp v40, v40, v40 row_ror:4 row_mask:0xf bank_mask:0xf bound_ctrl:1
	v_add_f32_dpp v2, v2, v2 row_ror:8 row_mask:0xf bank_mask:0xf bound_ctrl:1
	v_cndmask_b32_e64 v41, v56, v2, s[28:29]
	v_add_f32_dpp v40, v40, v40 row_ror:8 row_mask:0xf bank_mask:0xf bound_ctrl:1
	ds_read_b128 v[160:163], v124 offset:18304
	ds_read_b128 v[164:167], v124 offset:18560
	ds_read_b128 v[168:171], v124 offset:18816
	ds_read_b128 v[172:175], v124 offset:19072
	ds_read_b128 v[176:179], v124 offset:19328
	ds_read_b32 v158, v110 offset:19584
	v_pk_fma_f32 v[106:107], v[192:193], v[40:41], v[32:33] op_sel_hi:[1,0,1]
	v_pk_fma_f32 v[34:35], v[202:203], v[208:209], v[34:35] op_sel_hi:[1,0,1]
	s_waitcnt lgkmcnt(11)
	v_mul_f32_e32 v125, v136, v106
	v_pk_fma_f32 v[108:109], v[194:195], v[40:41], v[34:35] op_sel_hi:[1,0,1]
	v_fmac_f32_e32 v125, v107, v137
	v_fmac_f32_e32 v125, v108, v138
	v_fmac_f32_e32 v125, v109, v139
	s_waitcnt lgkmcnt(9)
	v_pk_mul_f32 v[52:53], v[144:145], v[106:107]
	v_pk_mul_f32 v[54:55], v[146:147], v[108:109]
	s_waitcnt lgkmcnt(6)
	v_pk_fma_f32 v[44:45], v[148:149], v[156:157], v[52:53] op_sel_hi:[1,0,1]
	v_pk_fma_f32 v[46:47], v[150:151], v[156:157], v[54:55] op_sel_hi:[1,0,1]
	v_add_f32_dpp v2, v125, v125 quad_perm:[1,0,3,2] row_mask:0xf bank_mask:0xf bound_ctrl:1
	v_mul_f32_e32 v32, v204, v106
	v_fmac_f32_e32 v32, v107, v205
	v_add_f32_dpp v2, v2, v2 quad_perm:[2,3,0,1] row_mask:0xf bank_mask:0xf bound_ctrl:1
	v_fmac_f32_e32 v32, v108, v206
	v_fmac_f32_e32 v32, v109, v207
	v_add_f32_dpp v2, v2, v2 row_ror:4 row_mask:0xf bank_mask:0xf bound_ctrl:1
	s_nop 0
	v_add_f32_dpp v32, v32, v32 quad_perm:[1,0,3,2] row_mask:0xf bank_mask:0xf bound_ctrl:1
	v_add_f32_dpp v2, v2, v2 row_ror:8 row_mask:0xf bank_mask:0xf bound_ctrl:1
	v_pk_fma_f32 v[106:107], v[140:141], v[2:3], v[44:45] op_sel_hi:[1,0,1]
	v_pk_fma_f32 v[108:109], v[142:143], v[2:3], v[46:47] op_sel_hi:[1,0,1]
	v_mul_f32_e32 v2, v152, v106
	v_add_f32_dpp v32, v32, v32 quad_perm:[2,3,0,1] row_mask:0xf bank_mask:0xf bound_ctrl:1
	v_fmac_f32_e32 v2, v107, v153
	v_fmac_f32_e32 v2, v108, v154
	v_add_f32_dpp v32, v32, v32 row_ror:4 row_mask:0xf bank_mask:0xf bound_ctrl:1
	v_fmac_f32_e32 v2, v109, v155
	s_nop 0
	v_add_f32_dpp v32, v32, v32 row_ror:8 row_mask:0xf bank_mask:0xf bound_ctrl:1
	v_cndmask_b32_e64 v123, v41, v32, s[30:31]
	ds_read_b128 v[188:191], v124 offset:19712
	ds_read_b128 v[192:195], v124 offset:19968
	ds_read_b128 v[196:199], v124 offset:20224
	ds_read_b128 v[200:203], v124 offset:20480
	ds_read_b128 v[204:207], v124 offset:20736
	ds_read_b32 v208, v110 offset:20992
	v_add_f32_dpp v2, v2, v2 quad_perm:[1,0,3,2] row_mask:0xf bank_mask:0xf bound_ctrl:1
	s_waitcnt lgkmcnt(11)
; #define LAS __attribute__((address_space(3)))
; __device__ __forceinline__ float row16_sum(float x) { x += dpp_mov<0xB1>(x); x += dpp_mov<0x4E>(x); x += dpp_mov<0x124>(x); x += dpp_mov<0x128>(x); return x; }
; __device__ __forceinline__ void scan_phase(const KAS Args& a, LAS unsigned char* lds, int i, const int tid_, const int bid, const int nblk) {
;     ...
;                 const LAS float* sb = buf + 4 * cgp; const LAS float* vb = buf + 320 + rl;
;                 f32x4 kk4 = *(const LAS f32x4*)(sb), nb4 = *(const LAS f32x4*)(sb + 64), w4 = *(const LAS f32x4*)(sb + 128), k4 = *(const LAS f32x4*)(sb + 192), r4 = *(const LAS f32x4*)(sb + 256);
;                 float v = vb[0], ysel = 0.f;
; #pragma unroll
;                 for (int t = 0; t < TC; ++t) {
;                     f32x4 kk4n = kk4, nb4n = nb4, w4n = w4, k4n = k4, r4n = r4; float vn = v;
;                     if (t + 1 < TC) { const LAS float* sn = sb + (t + 1) * SST;
;                         kk4n = *(const LAS f32x4*)(sn); nb4n = *(const LAS f32x4*)(sn + 64); w4n = *(const LAS f32x4*)(sn + 128); k4n = *(const LAS f32x4*)(sn + 192); r4n = *(const LAS f32x4*)(sn + 256); vn = vb[(t + 1) * SST]; }
;                     __builtin_amdgcn_sched_barrier(0x6);
;                     float sa = fmaf(S[3], kk4[3], fmaf(S[2], kk4[2], fmaf(S[1], kk4[1], S[0] * kk4[0])));
;                     const f32x4 Tm = S * w4 + k4 * v;
;                     sa = row16_sum(sa);
;                     S = Tm + nb4 * sa;
;                     float y = fmaf(S[3], r4[3], fmaf(S[2], r4[2], fmaf(S[1], r4[1], S[0] * r4[0]))); y = row16_sum(y);
;                     ysel = (cgp == (t & 15)) ? y : ysel;
;                     if ((t & 15) == 15) yb[(t - 15 + cgp) * 32 + rl] = ysel;
;                     kk4 = kk4n; nb4 = nb4n; w4 = w4n; k4 = k4n; r4 = r4n; v = vn; }
	v_mul_f32_e32 v125, v160, v106
	v_fmac_f32_e32 v125, v107, v161
	v_add_f32_dpp v2, v2, v2 quad_perm:[2,3,0,1] row_mask:0xf bank_mask:0xf bound_ctrl:1
	v_fmac_f32_e32 v125, v108, v162
	v_fmac_f32_e32 v125, v109, v163
	v_add_f32_dpp v2, v2, v2 row_ror:4 row_mask:0xf bank_mask:0xf bound_ctrl:1
	s_waitcnt lgkmcnt(9)
	v_pk_mul_f32 v[60:61], v[168:169], v[106:107]
	v_pk_mul_f32 v[62:63], v[170:171], v[108:109]
	v_add_f32_dpp v2, v2, v2 row_ror:8 row_mask:0xf bank_mask:0xf bound_ctrl:1
	v_cndmask_b32_e64 v123, v123, v2, s[34:35]
	s_waitcnt lgkmcnt(6)
	v_pk_fma_f32 v[48:49], v[172:173], v[158:159], v[60:61] op_sel_hi:[1,0,1]
	v_add_f32_dpp v60, v125, v125 quad_perm:[1,0,3,2] row_mask:0xf bank_mask:0xf bound_ctrl:1
	ds_read_b128 v[136:139], v124 offset:21120
	ds_read_b128 v[140:143], v124 offset:21376
	ds_read_b128 v[144:147], v124 offset:21632
	ds_read_b128 v[148:151], v124 offset:21888
	ds_read_b128 v[152:155], v124 offset:22144
	ds_read_b32 v156, v110 offset:22400
	v_add_f32_dpp v60, v60, v60 quad_perm:[2,3,0,1] row_mask:0xf bank_mask:0xf bound_ctrl:1
	v_pk_fma_f32 v[50:51], v[174:175], v[158:159], v[62:63] op_sel_hi:[1,0,1]
	s_nop 0
	v_add_f32_dpp v60, v60, v60 row_ror:4 row_mask:0xf bank_mask:0xf bound_ctrl:1
	s_nop 1
	v_add_f32_dpp v60, v60, v60 row_ror:8 row_mask:0xf bank_mask:0xf bound_ctrl:1
	v_pk_fma_f32 v[106:107], v[164:165], v[60:61], v[48:49] op_sel_hi:[1,0,1]
	v_pk_fma_f32 v[108:109], v[166:167], v[60:61], v[50:51] op_sel_hi:[1,0,1]
	s_waitcnt lgkmcnt(11)
	v_mul_f32_e32 v125, v188, v106
	v_fmac_f32_e32 v125, v107, v189
	v_fmac_f32_e32 v125, v108, v190
	v_fmac_f32_e32 v125, v109, v191
	s_waitcnt lgkmcnt(9)
	v_pk_mul_f32 v[52:53], v[196:197], v[106:107]
	v_pk_mul_f32 v[54:55], v[198:199], v[108:109]
	s_waitcnt lgkmcnt(6)
	v_pk_fma_f32 v[44:45], v[200:201], v[208:209], v[52:53] op_sel_hi:[1,0,1]
	v_pk_fma_f32 v[46:47], v[202:203], v[208:209], v[54:55] op_sel_hi:[1,0,1]
	v_add_f32_dpp v2, v125, v125 quad_perm:[1,0,3,2] row_mask:0xf bank_mask:0xf bound_ctrl:1
	v_mul_f32_e32 v32, v176, v106
	v_fmac_f32_e32 v32, v107, v177
	v_add_f32_dpp v2, v2, v2 quad_perm:[2,3,0,1] row_mask:0xf bank_mask:0xf bound_ctrl:1
	v_fmac_f32_e32 v32, v108, v178
	v_fmac_f32_e32 v32, v109, v179
	v_add_f32_dpp v2, v2, v2 row_ror:4 row_mask:0xf bank_mask:0xf bound_ctrl:1
	s_nop 0
	v_add_f32_dpp v32, v32, v32 quad_perm:[1,0,3,2] row_mask:0xf bank_mask:0xf bound_ctrl:1
	v_add_f32_dpp v2, v2, v2 row_ror:8 row_mask:0xf bank_mask:0xf bound_ctrl:1
	v_pk_fma_f32 v[106:107], v[192:193], v[2:3], v[44:45] op_sel_hi:[1,0,1]
	v_pk_fma_f32 v[108:109], v[194:195], v[2:3], v[46:47] op_sel_hi:[1,0,1]
	v_mul_f32_e32 v2, v204, v106
	v_add_f32_dpp v32, v32, v32 quad_perm:[2,3,0,1] row_mask:0xf bank_mask:0xf bound_ctrl:1
	v_fmac_f32_e32 v2, v107, v205
	v_fmac_f32_e32 v2, v108, v206
	v_add_f32_dpp v32, v32, v32 row_ror:4 row_mask:0xf bank_mask:0xf bound_ctrl:1
	v_fmac_f32_e32 v2, v109, v207
	s_nop 0
	v_add_f32_dpp v32, v32, v32 row_ror:8 row_mask:0xf bank_mask:0xf bound_ctrl:1
	v_cndmask_b32_e64 v123, v123, v32, s[36:37]
	ds_read_b128 v[160:163], v124 offset:22528
	ds_read_b128 v[164:167], v124 offset:22784
	ds_read_b128 v[168:171], v124 offset:23040
	ds_read_b128 v[172:175], v124 offset:23296
	ds_read_b128 v[176:179], v124 offset:23552
	ds_read_b32 v158, v110 offset:23808
	v_add_f32_dpp v2, v2, v2 quad_perm:[1,0,3,2] row_mask:0xf bank_mask:0xf bound_ctrl:1
	s_waitcnt lgkmcnt(11)
	v_mul_f32_e32 v125, v136, v106
	v_fmac_f32_e32 v125, v107, v137
	v_add_f32_dpp v2, v2, v2 quad_perm:[2,3,0,1] row_mask:0xf bank_mask:0xf bound_ctrl:1
	v_fmac_f32_e32 v125, v108, v138
	v_fmac_f32_e32 v125, v109, v139
	v_add_f32_dpp v2, v2, v2 row_ror:4 row_mask:0xf bank_mask:0xf bound_ctrl:1
	s_waitcnt lgkmcnt(9)
	v_pk_mul_f32 v[60:61], v[144:145], v[106:107]
	v_pk_mul_f32 v[62:63], v[146:147], v[108:109]
	v_add_f32_dpp v2, v2, v2 row_ror:8 row_mask:0xf bank_mask:0xf bound_ctrl:1
	v_cndmask_b32_e64 v123, v123, v2, s[38:39]
	s_waitcnt lgkmcnt(6)
	v_pk_fma_f32 v[48:49], v[148:149], v[156:157], v[60:61] op_sel_hi:[1,0,1]
	v_add_f32_dpp v60, v125, v125 quad_perm:[1,0,3,2] row_mask:0xf bank_mask:0xf bound_ctrl:1
	ds_read_b128 v[188:191], v124 offset:23936
	ds_read_b128 v[192:195], v124 offset:24192
	ds_read_b128 v[196:199], v124 offset:24448
	ds_read_b128 v[200:203], v124 offset:24704
	ds_read_b128 v[204:207], v124 offset:24960
	ds_read_b32 v208, v110 offset:25216
	v_add_f32_dpp v60, v60, v60 quad_perm:[2,3,0,1] row_mask:0xf bank_mask:0xf bound_ctrl:1
	v_pk_fma_f32 v[50:51], v[150:151], v[156:157], v[62:63] op_sel_hi:[1,0,1]
	v_add3_u32 v122, s63, v120, v118
	v_add_f32_dpp v60, v60, v60 row_ror:4 row_mask:0xf bank_mask:0xf bound_ctrl:1
	s_nop 1
	v_add_f32_dpp v60, v60, v60 row_ror:8 row_mask:0xf bank_mask:0xf bound_ctrl:1
	v_pk_fma_f32 v[106:107], v[140:141], v[60:61], v[48:49] op_sel_hi:[1,0,1]
	v_pk_fma_f32 v[108:109], v[142:143], v[60:61], v[50:51] op_sel_hi:[1,0,1]
	v_mul_f32_e32 v32, v152, v106
	v_fmac_f32_e32 v32, v107, v153
	s_waitcnt lgkmcnt(11)
	v_mul_f32_e32 v125, v160, v106
	v_fmac_f32_e32 v32, v108, v154
	v_fmac_f32_e32 v125, v107, v161
	v_fmac_f32_e32 v32, v109, v155
	v_fmac_f32_e32 v125, v108, v162
	v_fmac_f32_e32 v125, v109, v163
	v_add_f32_dpp v32, v32, v32 quad_perm:[1,0,3,2] row_mask:0xf bank_mask:0xf bound_ctrl:1
	s_waitcnt lgkmcnt(9)
	v_pk_mul_f32 v[28:29], v[168:169], v[106:107]
	v_pk_mul_f32 v[30:31], v[170:171], v[108:109]
	v_add_f32_dpp v32, v32, v32 quad_perm:[2,3,0,1] row_mask:0xf bank_mask:0xf bound_ctrl:1
	s_waitcnt lgkmcnt(6)
; #define LAS __attribute__((address_space(3)))
; __device__ __forceinline__ float row16_sum(float x) { x += dpp_mov<0xB1>(x); x += dpp_mov<0x4E>(x); x += dpp_mov<0x124>(x); x += dpp_mov<0x128>(x); return x; }
; __device__ __forceinline__ void scan_phase(const KAS Args& a, LAS unsigned char* lds, int i, const int tid_, const int bid, const int nblk) {
;     ...
;                 const LAS float* sb = buf + 4 * cgp; const LAS float* vb = buf + 320 + rl;
;                 f32x4 kk4 = *(const LAS f32x4*)(sb), nb4 = *(const LAS f32x4*)(sb + 64), w4 = *(const LAS f32x4*)(sb + 128), k4 = *(const LAS f32x4*)(sb + 192), r4 = *(const LAS f32x4*)(sb + 256);
;                 float v = vb[0], ysel = 0.f;
; #pragma unroll
;                 for (int t = 0; t < TC; ++t) {
;                     f32x4 kk4n = kk4, nb4n = nb4, w4n = w4, k4n = k4, r4n = r4; float vn = v;
;                     if (t + 1 < TC) { const LAS float* sn = sb + (t + 1) * SST;
;                         kk4n = *(const LAS f32x4*)(sn); nb4n = *(const LAS f32x4*)(sn + 64); w4n = *(const LAS f32x4*)(sn + 128); k4n = *(const LAS f32x4*)(sn + 192); r4n = *(const LAS f32x4*)(sn + 256); vn = vb[(t + 1) * SST]; }
;                     __builtin_amdgcn_sched_barrier(0x6);
;                     float sa = fmaf(S[3], kk4[3], fmaf(S[2], kk4[2], fmaf(S[1], kk4[1], S[0] * kk4[0])));
;                     const f32x4 Tm = S * w4 + k4 * v;
;                     sa = row16_sum(sa);
;                     S = Tm + nb4 * sa;
;                     float y = fmaf(S[3], r4[3], fmaf(S[2], r4[2], fmaf(S[1], r4[1], S[0] * r4[0]))); y = row16_sum(y);
;                     ysel = (cgp == (t & 15)) ? y : ysel;
;                     if ((t & 15) == 15) yb[(t - 15 + cgp) * 32 + rl] = ysel;
;                     kk4 = kk4n; nb4 = nb4n; w4 = w4n; k4 = k4n; r4 = r4n; v = vn; }
	v_pk_fma_f32 v[30:31], v[174:175], v[158:159], v[30:31] op_sel_hi:[1,0,1]
	v_pk_fma_f32 v[28:29], v[172:173], v[158:159], v[28:29] op_sel_hi:[1,0,1]
	v_add_f32_dpp v2, v125, v125 quad_perm:[1,0,3,2] row_mask:0xf bank_mask:0xf bound_ctrl:1
	v_add_f32_dpp v32, v32, v32 row_ror:4 row_mask:0xf bank_mask:0xf bound_ctrl:1
	s_nop 0
	v_add_f32_dpp v2, v2, v2 quad_perm:[2,3,0,1] row_mask:0xf bank_mask:0xf bound_ctrl:1
	v_add_f32_dpp v32, v32, v32 row_ror:8 row_mask:0xf bank_mask:0xf bound_ctrl:1
	v_cndmask_b32_e64 v123, v123, v32, s[40:41]
	v_add_f32_dpp v2, v2, v2 row_ror:4 row_mask:0xf bank_mask:0xf bound_ctrl:1
	ds_write_b32 v122, v123
	ds_read_b128 v[136:139], v124 offset:25344
	ds_read_b128 v[140:143], v124 offset:25600
	ds_read_b128 v[144:147], v124 offset:25856
	ds_read_b128 v[148:151], v124 offset:26112
	ds_read_b128 v[152:155], v124 offset:26368
	ds_read_b32 v156, v110 offset:26624
	v_add_f32_dpp v2, v2, v2 row_ror:8 row_mask:0xf bank_mask:0xf bound_ctrl:1
	v_pk_fma_f32 v[106:107], v[164:165], v[2:3], v[28:29] op_sel_hi:[1,0,1]
	v_pk_fma_f32 v[108:109], v[166:167], v[2:3], v[30:31] op_sel_hi:[1,0,1]
	v_mul_f32_e32 v2, v176, v106
	s_waitcnt lgkmcnt(12)
	v_mul_f32_e32 v125, v188, v106
	v_fmac_f32_e32 v2, v107, v177
	v_fmac_f32_e32 v125, v107, v189
	v_fmac_f32_e32 v2, v108, v178
	v_fmac_f32_e32 v125, v108, v190
	v_fmac_f32_e32 v2, v109, v179
	v_fmac_f32_e32 v125, v109, v191
	s_waitcnt lgkmcnt(10)
	v_pk_mul_f32 v[32:33], v[196:197], v[106:107]
	v_add_f32_dpp v2, v2, v2 quad_perm:[1,0,3,2] row_mask:0xf bank_mask:0xf bound_ctrl:1
	v_add_f32_dpp v48, v125, v125 quad_perm:[1,0,3,2] row_mask:0xf bank_mask:0xf bound_ctrl:1
	s_waitcnt lgkmcnt(7)
	v_pk_fma_f32 v[32:33], v[200:201], v[208:209], v[32:33] op_sel_hi:[1,0,1]
	v_add_f32_dpp v2, v2, v2 quad_perm:[2,3,0,1] row_mask:0xf bank_mask:0xf bound_ctrl:1
	v_add_f32_dpp v48, v48, v48 quad_perm:[2,3,0,1] row_mask:0xf bank_mask:0xf bound_ctrl:1
	v_pk_mul_f32 v[34:35], v[198:199], v[108:109]
	v_add_f32_dpp v2, v2, v2 row_ror:4 row_mask:0xf bank_mask:0xf bound_ctrl:1
	v_add_f32_dpp v48, v48, v48 row_ror:4 row_mask:0xf bank_mask:0xf bound_ctrl:1
	v_pk_fma_f32 v[34:35], v[202:203], v[208:209], v[34:35] op_sel_hi:[1,0,1]
	v_add_f32_dpp v2, v2, v2 row_ror:8 row_mask:0xf bank_mask:0xf bound_ctrl:1
	v_add_f32_dpp v48, v48, v48 row_ror:8 row_mask:0xf bank_mask:0xf bound_ctrl:1
	v_cndmask_b32_e64 v123, v123, v2, s[8:9]
	ds_read_b128 v[160:163], v124 offset:26752
	ds_read_b128 v[164:167], v124 offset:27008
	ds_read_b128 v[168:171], v124 offset:27264
	ds_read_b128 v[172:175], v124 offset:27520
	ds_read_b128 v[176:179], v124 offset:27776
	ds_read_b32 v158, v110 offset:28032
	v_pk_fma_f32 v[106:107], v[192:193], v[48:49], v[32:33] op_sel_hi:[1,0,1]
	v_pk_fma_f32 v[108:109], v[194:195], v[48:49], v[34:35] op_sel_hi:[1,0,1]
	s_waitcnt lgkmcnt(11)
	v_mul_f32_e32 v125, v136, v106
	v_mul_f32_e32 v32, v204, v106
	v_fmac_f32_e32 v125, v107, v137
	v_fmac_f32_e32 v32, v107, v205
	v_fmac_f32_e32 v125, v108, v138
	v_fmac_f32_e32 v32, v108, v206
	v_fmac_f32_e32 v125, v109, v139
	s_waitcnt lgkmcnt(9)
	v_pk_mul_f32 v[28:29], v[144:145], v[106:107]
	v_pk_mul_f32 v[30:31], v[146:147], v[108:109]
	v_fmac_f32_e32 v32, v109, v207
	s_waitcnt lgkmcnt(6)
	v_pk_fma_f32 v[30:31], v[150:151], v[156:157], v[30:31] op_sel_hi:[1,0,1]
	v_pk_fma_f32 v[28:29], v[148:149], v[156:157], v[28:29] op_sel_hi:[1,0,1]
	v_add_f32_dpp v2, v125, v125 quad_perm:[1,0,3,2] row_mask:0xf bank_mask:0xf bound_ctrl:1
	v_add_f32_dpp v32, v32, v32 quad_perm:[1,0,3,2] row_mask:0xf bank_mask:0xf bound_ctrl:1
	s_nop 0
	v_add_f32_dpp v2, v2, v2 quad_perm:[2,3,0,1] row_mask:0xf bank_mask:0xf bound_ctrl:1
	v_add_f32_dpp v32, v32, v32 quad_perm:[2,3,0,1] row_mask:0xf bank_mask:0xf bound_ctrl:1
	s_nop 0
	v_add_f32_dpp v2, v2, v2 row_ror:4 row_mask:0xf bank_mask:0xf bound_ctrl:1
	v_add_f32_dpp v32, v32, v32 row_ror:4 row_mask:0xf bank_mask:0xf bound_ctrl:1
	s_nop 0
	v_add_f32_dpp v2, v2, v2 row_ror:8 row_mask:0xf bank_mask:0xf bound_ctrl:1
	v_add_f32_dpp v32, v32, v32 row_ror:8 row_mask:0xf bank_mask:0xf bound_ctrl:1
	v_pk_fma_f32 v[106:107], v[140:141], v[2:3], v[28:29] op_sel_hi:[1,0,1]
	v_cndmask_b32_e64 v123, v123, v32, s[10:11]
	ds_read_b128 v[188:191], v124 offset:28160
	ds_read_b128 v[192:195], v124 offset:28416
	ds_read_b128 v[196:199], v124 offset:28672
	ds_read_b128 v[200:203], v124 offset:28928
	ds_read_b128 v[204:207], v124 offset:29184
	ds_read_b32 v208, v110 offset:29440
	v_pk_fma_f32 v[108:109], v[142:143], v[2:3], v[30:31] op_sel_hi:[1,0,1]
	v_mul_f32_e32 v2, v152, v106
	s_waitcnt lgkmcnt(11)
	v_mul_f32_e32 v125, v160, v106
	v_fmac_f32_e32 v2, v107, v153
	v_fmac_f32_e32 v125, v107, v161
	v_fmac_f32_e32 v2, v108, v154
	v_fmac_f32_e32 v125, v108, v162
	v_fmac_f32_e32 v2, v109, v155
	v_fmac_f32_e32 v125, v109, v163
	s_waitcnt lgkmcnt(9)
	v_pk_mul_f32 v[32:33], v[168:169], v[106:107]
	v_add_f32_dpp v2, v2, v2 quad_perm:[1,0,3,2] row_mask:0xf bank_mask:0xf bound_ctrl:1
	v_add_f32_dpp v48, v125, v125 quad_perm:[1,0,3,2] row_mask:0xf bank_mask:0xf bound_ctrl:1
	s_waitcnt lgkmcnt(6)
	v_pk_fma_f32 v[32:33], v[172:173], v[158:159], v[32:33] op_sel_hi:[1,0,1]
	v_add_f32_dpp v2, v2, v2 quad_perm:[2,3,0,1] row_mask:0xf bank_mask:0xf bound_ctrl:1
	v_add_f32_dpp v48, v48, v48 quad_perm:[2,3,0,1] row_mask:0xf bank_mask:0xf bound_ctrl:1
	v_pk_mul_f32 v[34:35], v[170:171], v[108:109]
	v_add_f32_dpp v2, v2, v2 row_ror:4 row_mask:0xf bank_mask:0xf bound_ctrl:1
	v_add_f32_dpp v48, v48, v48 row_ror:4 row_mask:0xf bank_mask:0xf bound_ctrl:1
	v_pk_fma_f32 v[34:35], v[174:175], v[158:159], v[34:35] op_sel_hi:[1,0,1]
	v_add_f32_dpp v2, v2, v2 row_ror:8 row_mask:0xf bank_mask:0xf bound_ctrl:1
	v_add_f32_dpp v48, v48, v48 row_ror:8 row_mask:0xf bank_mask:0xf bound_ctrl:1
	v_cndmask_b32_e64 v123, v123, v2, s[12:13]
	ds_read_b128 v[136:139], v124 offset:29568
	ds_read_b128 v[140:143], v124 offset:29824
	ds_read_b128 v[144:147], v124 offset:30080
	ds_read_b128 v[148:151], v124 offset:30336
	ds_read_b128 v[152:155], v124 offset:30592
	ds_read_b32 v156, v110 offset:30848
	v_pk_fma_f32 v[106:107], v[164:165], v[48:49], v[32:33] op_sel_hi:[1,0,1]
	v_pk_fma_f32 v[108:109], v[166:167], v[48:49], v[34:35] op_sel_hi:[1,0,1]
	s_waitcnt lgkmcnt(11)
; #define LAS __attribute__((address_space(3)))
; __device__ __forceinline__ float row16_sum(float x) { x += dpp_mov<0xB1>(x); x += dpp_mov<0x4E>(x); x += dpp_mov<0x124>(x); x += dpp_mov<0x128>(x); return x; }
; __device__ __forceinline__ void scan_phase(const KAS Args& a, LAS unsigned char* lds, int i, const int tid_, const int bid, const int nblk) {
;     ...
;                 const LAS float* sb = buf + 4 * cgp; const LAS float* vb = buf + 320 + rl;
;                 f32x4 kk4 = *(const LAS f32x4*)(sb), nb4 = *(const LAS f32x4*)(sb + 64), w4 = *(const LAS f32x4*)(sb + 128), k4 = *(const LAS f32x4*)(sb + 192), r4 = *(const LAS f32x4*)(sb + 256);
;                 float v = vb[0], ysel = 0.f;
; #pragma unroll
;                 for (int t = 0; t < TC; ++t) {
;                     f32x4 kk4n = kk4, nb4n = nb4, w4n = w4, k4n = k4, r4n = r4; float vn = v;
;                     if (t + 1 < TC) { const LAS float* sn = sb + (t + 1) * SST;
;                         kk4n = *(const LAS f32x4*)(sn); nb4n = *(const LAS f32x4*)(sn + 64); w4n = *(const LAS f32x4*)(sn + 128); k4n = *(const LAS f32x4*)(sn + 192); r4n = *(const LAS f32x4*)(sn + 256); vn = vb[(t + 1) * SST]; }
;                     __builtin_amdgcn_sched_barrier(0x6);
;                     float sa = fmaf(S[3], kk4[3], fmaf(S[2], kk4[2], fmaf(S[1], kk4[1], S[0] * kk4[0])));
;                     const f32x4 Tm = S * w4 + k4 * v;
;                     sa = row16_sum(sa);
;                     S = Tm + nb4 * sa;
;                     float y = fmaf(S[3], r4[3], fmaf(S[2], r4[2], fmaf(S[1], r4[1], S[0] * r4[0]))); y = row16_sum(y);
;                     ysel = (cgp == (t & 15)) ? y : ysel;
;                     if ((t & 15) == 15) yb[(t - 15 + cgp) * 32 + rl] = ysel;
;                     kk4 = kk4n; nb4 = nb4n; w4 = w4n; k4 = k4n; r4 = r4n; v = vn; }
	v_mul_f32_e32 v125, v188, v106
	v_mul_f32_e32 v32, v176, v106
	v_fmac_f32_e32 v125, v107, v189
	v_fmac_f32_e32 v32, v107, v177
	v_fmac_f32_e32 v125, v108, v190
	v_fmac_f32_e32 v32, v108, v178
	v_fmac_f32_e32 v125, v109, v191
	s_waitcnt lgkmcnt(9)
	v_pk_mul_f32 v[28:29], v[196:197], v[106:107]
	v_pk_mul_f32 v[30:31], v[198:199], v[108:109]
	v_fmac_f32_e32 v32, v109, v179
	s_waitcnt lgkmcnt(6)
	v_pk_fma_f32 v[30:31], v[202:203], v[208:209], v[30:31] op_sel_hi:[1,0,1]
	v_pk_fma_f32 v[28:29], v[200:201], v[208:209], v[28:29] op_sel_hi:[1,0,1]
	v_add_f32_dpp v2, v125, v125 quad_perm:[1,0,3,2] row_mask:0xf bank_mask:0xf bound_ctrl:1
	v_add_f32_dpp v32, v32, v32 quad_perm:[1,0,3,2] row_mask:0xf bank_mask:0xf bound_ctrl:1
	s_nop 0
	v_add_f32_dpp v2, v2, v2 quad_perm:[2,3,0,1] row_mask:0xf bank_mask:0xf bound_ctrl:1
	v_add_f32_dpp v32, v32, v32 quad_perm:[2,3,0,1] row_mask:0xf bank_mask:0xf bound_ctrl:1
	s_nop 0
	v_add_f32_dpp v2, v2, v2 row_ror:4 row_mask:0xf bank_mask:0xf bound_ctrl:1
	v_add_f32_dpp v32, v32, v32 row_ror:4 row_mask:0xf bank_mask:0xf bound_ctrl:1
	s_nop 0
	v_add_f32_dpp v2, v2, v2 row_ror:8 row_mask:0xf bank_mask:0xf bound_ctrl:1
	v_add_f32_dpp v32, v32, v32 row_ror:8 row_mask:0xf bank_mask:0xf bound_ctrl:1
	v_pk_fma_f32 v[106:107], v[192:193], v[2:3], v[28:29] op_sel_hi:[1,0,1]
	v_cndmask_b32_e64 v123, v123, v32, s[14:15]
	ds_read_b128 v[160:163], v124 offset:30976
	ds_read_b128 v[164:167], v124 offset:31232
	ds_read_b128 v[168:171], v124 offset:31488
	ds_read_b128 v[172:175], v124 offset:31744
	ds_read_b128 v[176:179], v124 offset:32000
	ds_read_b32 v158, v110 offset:32256
	v_pk_fma_f32 v[108:109], v[194:195], v[2:3], v[30:31] op_sel_hi:[1,0,1]
	v_mul_f32_e32 v2, v204, v106
	s_waitcnt lgkmcnt(11)
	v_mul_f32_e32 v125, v136, v106
	v_fmac_f32_e32 v2, v107, v205
	v_fmac_f32_e32 v125, v107, v137
	v_fmac_f32_e32 v2, v108, v206
	v_fmac_f32_e32 v125, v108, v138
	v_fmac_f32_e32 v2, v109, v207
	v_fmac_f32_e32 v125, v109, v139
	s_waitcnt lgkmcnt(9)
	v_pk_mul_f32 v[32:33], v[144:145], v[106:107]
	v_add_f32_dpp v2, v2, v2 quad_perm:[1,0,3,2] row_mask:0xf bank_mask:0xf bound_ctrl:1
	v_add_f32_dpp v48, v125, v125 quad_perm:[1,0,3,2] row_mask:0xf bank_mask:0xf bound_ctrl:1
	s_waitcnt lgkmcnt(6)
	v_pk_fma_f32 v[32:33], v[148:149], v[156:157], v[32:33] op_sel_hi:[1,0,1]
	v_add_f32_dpp v2, v2, v2 quad_perm:[2,3,0,1] row_mask:0xf bank_mask:0xf bound_ctrl:1
	v_add_f32_dpp v48, v48, v48 quad_perm:[2,3,0,1] row_mask:0xf bank_mask:0xf bound_ctrl:1
	v_pk_mul_f32 v[34:35], v[146:147], v[108:109]
	v_add_f32_dpp v2, v2, v2 row_ror:4 row_mask:0xf bank_mask:0xf bound_ctrl:1
	v_add_f32_dpp v48, v48, v48 row_ror:4 row_mask:0xf bank_mask:0xf bound_ctrl:1
	v_pk_fma_f32 v[34:35], v[150:151], v[156:157], v[34:35] op_sel_hi:[1,0,1]
	v_add_f32_dpp v2, v2, v2 row_ror:8 row_mask:0xf bank_mask:0xf bound_ctrl:1
	v_add_f32_dpp v48, v48, v48 row_ror:8 row_mask:0xf bank_mask:0xf bound_ctrl:1
	v_cndmask_b32_e64 v123, v123, v2, s[16:17]
	ds_read_b128 v[188:191], v124 offset:32384
	ds_read_b128 v[192:195], v124 offset:32640
	ds_read_b128 v[196:199], v124 offset:32896
	ds_read_b128 v[200:203], v124 offset:33152
	ds_read_b128 v[204:207], v124 offset:33408
	ds_read_b32 v208, v110 offset:33664
	v_pk_fma_f32 v[106:107], v[140:141], v[48:49], v[32:33] op_sel_hi:[1,0,1]
	v_pk_fma_f32 v[108:109], v[142:143], v[48:49], v[34:35] op_sel_hi:[1,0,1]
	s_waitcnt lgkmcnt(11)
	v_mul_f32_e32 v125, v160, v106
	v_mul_f32_e32 v32, v152, v106
	v_fmac_f32_e32 v125, v107, v161
	v_fmac_f32_e32 v32, v107, v153
	v_fmac_f32_e32 v125, v108, v162
	v_fmac_f32_e32 v32, v108, v154
	v_fmac_f32_e32 v125, v109, v163
	s_waitcnt lgkmcnt(9)
	v_pk_mul_f32 v[28:29], v[168:169], v[106:107]
	v_pk_mul_f32 v[30:31], v[170:171], v[108:109]
	v_fmac_f32_e32 v32, v109, v155
	s_waitcnt lgkmcnt(6)
	v_pk_fma_f32 v[30:31], v[174:175], v[158:159], v[30:31] op_sel_hi:[1,0,1]
	v_pk_fma_f32 v[28:29], v[172:173], v[158:159], v[28:29] op_sel_hi:[1,0,1]
	v_add_f32_dpp v2, v125, v125 quad_perm:[1,0,3,2] row_mask:0xf bank_mask:0xf bound_ctrl:1
	v_add_f32_dpp v32, v32, v32 quad_perm:[1,0,3,2] row_mask:0xf bank_mask:0xf bound_ctrl:1
	s_nop 0
	v_add_f32_dpp v2, v2, v2 quad_perm:[2,3,0,1] row_mask:0xf bank_mask:0xf bound_ctrl:1
	v_add_f32_dpp v32, v32, v32 quad_perm:[2,3,0,1] row_mask:0xf bank_mask:0xf bound_ctrl:1
	s_nop 0
	v_add_f32_dpp v2, v2, v2 row_ror:4 row_mask:0xf bank_mask:0xf bound_ctrl:1
	v_add_f32_dpp v32, v32, v32 row_ror:4 row_mask:0xf bank_mask:0xf bound_ctrl:1
	s_nop 0
	v_add_f32_dpp v2, v2, v2 row_ror:8 row_mask:0xf bank_mask:0xf bound_ctrl:1
	v_add_f32_dpp v32, v32, v32 row_ror:8 row_mask:0xf bank_mask:0xf bound_ctrl:1
	v_pk_fma_f32 v[106:107], v[164:165], v[2:3], v[28:29] op_sel_hi:[1,0,1]
	v_cndmask_b32_e64 v123, v123, v32, s[18:19]
	ds_read_b128 v[136:139], v124 offset:33792
	ds_read_b128 v[140:143], v124 offset:34048
	ds_read_b128 v[144:147], v124 offset:34304
	ds_read_b128 v[148:151], v124 offset:34560
	ds_read_b128 v[152:155], v124 offset:34816
	ds_read_b32 v156, v110 offset:35072
	v_pk_fma_f32 v[108:109], v[166:167], v[2:3], v[30:31] op_sel_hi:[1,0,1]
	v_mul_f32_e32 v2, v176, v106
	s_waitcnt lgkmcnt(11)
	v_mul_f32_e32 v125, v188, v106
	v_fmac_f32_e32 v2, v107, v177
	v_fmac_f32_e32 v125, v107, v189
	v_fmac_f32_e32 v2, v108, v178
	v_fmac_f32_e32 v125, v108, v190
	v_fmac_f32_e32 v2, v109, v179
	v_fmac_f32_e32 v125, v109, v191
	s_waitcnt lgkmcnt(9)
	v_pk_mul_f32 v[32:33], v[196:197], v[106:107]
	v_add_f32_dpp v2, v2, v2 quad_perm:[1,0,3,2] row_mask:0xf bank_mask:0xf bound_ctrl:1
	v_add_f32_dpp v48, v125, v125 quad_perm:[1,0,3,2] row_mask:0xf bank_mask:0xf bound_ctrl:1
	s_waitcnt lgkmcnt(6)
; #define LAS __attribute__((address_space(3)))
; __device__ __forceinline__ float row16_sum(float x) { x += dpp_mov<0xB1>(x); x += dpp_mov<0x4E>(x); x += dpp_mov<0x124>(x); x += dpp_mov<0x128>(x); return x; }
; __device__ __forceinline__ void scan_phase(const KAS Args& a, LAS unsigned char* lds, int i, const int tid_, const int bid, const int nblk) {
;     ...
;                 const LAS float* sb = buf + 4 * cgp; const LAS float* vb = buf + 320 + rl;
;                 f32x4 kk4 = *(const LAS f32x4*)(sb), nb4 = *(const LAS f32x4*)(sb + 64), w4 = *(const LAS f32x4*)(sb + 128), k4 = *(const LAS f32x4*)(sb + 192), r4 = *(const LAS f32x4*)(sb + 256);
;                 float v = vb[0], ysel = 0.f;
; #pragma unroll
;                 for (int t = 0; t < TC; ++t) {
;                     f32x4 kk4n = kk4, nb4n = nb4, w4n = w4, k4n = k4, r4n = r4; float vn = v;
;                     if (t + 1 < TC) { const LAS float* sn = sb + (t + 1) * SST;
;                         kk4n = *(const LAS f32x4*)(sn); nb4n = *(const LAS f32x4*)(sn + 64); w4n = *(const LAS f32x4*)(sn + 128); k4n = *(const LAS f32x4*)(sn + 192); r4n = *(const LAS f32x4*)(sn + 256); vn = vb[(t + 1) * SST]; }
;                     __builtin_amdgcn_sched_barrier(0x6);
;                     float sa = fmaf(S[3], kk4[3], fmaf(S[2], kk4[2], fmaf(S[1], kk4[1], S[0] * kk4[0])));
;                     const f32x4 Tm = S * w4 + k4 * v;
;                     sa = row16_sum(sa);
;                     S = Tm + nb4 * sa;
;                     float y = fmaf(S[3], r4[3], fmaf(S[2], r4[2], fmaf(S[1], r4[1], S[0] * r4[0]))); y = row16_sum(y);
;                     ysel = (cgp == (t & 15)) ? y : ysel;
;                     if ((t & 15) == 15) yb[(t - 15 + cgp) * 32 + rl] = ysel;
;                     kk4 = kk4n; nb4 = nb4n; w4 = w4n; k4 = k4n; r4 = r4n; v = vn; }
	v_pk_fma_f32 v[32:33], v[200:201], v[208:209], v[32:33] op_sel_hi:[1,0,1]
	v_add_f32_dpp v2, v2, v2 quad_perm:[2,3,0,1] row_mask:0xf bank_mask:0xf bound_ctrl:1
	v_add_f32_dpp v48, v48, v48 quad_perm:[2,3,0,1] row_mask:0xf bank_mask:0xf bound_ctrl:1
	v_pk_mul_f32 v[34:35], v[198:199], v[108:109]
	v_add_f32_dpp v2, v2, v2 row_ror:4 row_mask:0xf bank_mask:0xf bound_ctrl:1
	v_add_f32_dpp v48, v48, v48 row_ror:4 row_mask:0xf bank_mask:0xf bound_ctrl:1
	v_pk_fma_f32 v[34:35], v[202:203], v[208:209], v[34:35] op_sel_hi:[1,0,1]
	v_add_f32_dpp v2, v2, v2 row_ror:8 row_mask:0xf bank_mask:0xf bound_ctrl:1
	v_add_f32_dpp v48, v48, v48 row_ror:8 row_mask:0xf bank_mask:0xf bound_ctrl:1
	v_cndmask_b32_e64 v123, v123, v2, s[20:21]
	ds_read_b128 v[160:163], v124 offset:35200
	ds_read_b128 v[164:167], v124 offset:35456
	ds_read_b128 v[168:171], v124 offset:35712
	ds_read_b128 v[172:175], v124 offset:35968
	ds_read_b128 v[176:179], v124 offset:36224
	ds_read_b32 v158, v110 offset:36480
	v_pk_fma_f32 v[106:107], v[192:193], v[48:49], v[32:33] op_sel_hi:[1,0,1]
	v_pk_fma_f32 v[108:109], v[194:195], v[48:49], v[34:35] op_sel_hi:[1,0,1]
	s_waitcnt lgkmcnt(11)
	v_mul_f32_e32 v125, v136, v106
	v_mul_f32_e32 v32, v204, v106
	v_fmac_f32_e32 v125, v107, v137
	v_fmac_f32_e32 v32, v107, v205
	v_fmac_f32_e32 v125, v108, v138
	v_fmac_f32_e32 v32, v108, v206
	v_fmac_f32_e32 v125, v109, v139
	s_waitcnt lgkmcnt(9)
	v_pk_mul_f32 v[28:29], v[144:145], v[106:107]
	v_pk_mul_f32 v[30:31], v[146:147], v[108:109]
	v_fmac_f32_e32 v32, v109, v207
	s_waitcnt lgkmcnt(6)
	v_pk_fma_f32 v[30:31], v[150:151], v[156:157], v[30:31] op_sel_hi:[1,0,1]
	v_pk_fma_f32 v[28:29], v[148:149], v[156:157], v[28:29] op_sel_hi:[1,0,1]
	v_add_f32_dpp v2, v125, v125 quad_perm:[1,0,3,2] row_mask:0xf bank_mask:0xf bound_ctrl:1
	v_add_f32_dpp v32, v32, v32 quad_perm:[1,0,3,2] row_mask:0xf bank_mask:0xf bound_ctrl:1
	s_nop 0
	v_add_f32_dpp v2, v2, v2 quad_perm:[2,3,0,1] row_mask:0xf bank_mask:0xf bound_ctrl:1
	v_add_f32_dpp v32, v32, v32 quad_perm:[2,3,0,1] row_mask:0xf bank_mask:0xf bound_ctrl:1
	s_nop 0
	v_add_f32_dpp v2, v2, v2 row_ror:4 row_mask:0xf bank_mask:0xf bound_ctrl:1
	v_add_f32_dpp v32, v32, v32 row_ror:4 row_mask:0xf bank_mask:0xf bound_ctrl:1
	s_nop 0
	v_add_f32_dpp v2, v2, v2 row_ror:8 row_mask:0xf bank_mask:0xf bound_ctrl:1
	v_add_f32_dpp v32, v32, v32 row_ror:8 row_mask:0xf bank_mask:0xf bound_ctrl:1
	v_pk_fma_f32 v[106:107], v[140:141], v[2:3], v[28:29] op_sel_hi:[1,0,1]
	v_cndmask_b32_e64 v123, v123, v32, s[22:23]
	ds_read_b128 v[188:191], v124 offset:36608
	ds_read_b128 v[192:195], v124 offset:36864
	ds_read_b128 v[196:199], v124 offset:37120
	ds_read_b128 v[200:203], v124 offset:37376
	ds_read_b128 v[204:207], v124 offset:37632
	ds_read_b32 v208, v110 offset:37888
	v_pk_fma_f32 v[108:109], v[142:143], v[2:3], v[30:31] op_sel_hi:[1,0,1]
	v_mul_f32_e32 v2, v152, v106
	s_waitcnt lgkmcnt(11)
	v_mul_f32_e32 v125, v160, v106
	v_fmac_f32_e32 v2, v107, v153
	v_fmac_f32_e32 v125, v107, v161
	v_fmac_f32_e32 v2, v108, v154
	v_fmac_f32_e32 v125, v108, v162
	v_fmac_f32_e32 v2, v109, v155
	v_fmac_f32_e32 v125, v109, v163
	s_waitcnt lgkmcnt(9)
	v_pk_mul_f32 v[32:33], v[168:169], v[106:107]
	v_add_f32_dpp v2, v2, v2 quad_perm:[1,0,3,2] row_mask:0xf bank_mask:0xf bound_ctrl:1
	v_add_f32_dpp v48, v125, v125 quad_perm:[1,0,3,2] row_mask:0xf bank_mask:0xf bound_ctrl:1
	s_waitcnt lgkmcnt(6)
	v_pk_fma_f32 v[32:33], v[172:173], v[158:159], v[32:33] op_sel_hi:[1,0,1]
	v_add_f32_dpp v2, v2, v2 quad_perm:[2,3,0,1] row_mask:0xf bank_mask:0xf bound_ctrl:1
	v_add_f32_dpp v48, v48, v48 quad_perm:[2,3,0,1] row_mask:0xf bank_mask:0xf bound_ctrl:1
	v_pk_mul_f32 v[34:35], v[170:171], v[108:109]
	v_add_f32_dpp v2, v2, v2 row_ror:4 row_mask:0xf bank_mask:0xf bound_ctrl:1
	v_add_f32_dpp v48, v48, v48 row_ror:4 row_mask:0xf bank_mask:0xf bound_ctrl:1
	v_pk_fma_f32 v[34:35], v[174:175], v[158:159], v[34:35] op_sel_hi:[1,0,1]
	v_add_f32_dpp v2, v2, v2 row_ror:8 row_mask:0xf bank_mask:0xf bound_ctrl:1
	v_add_f32_dpp v48, v48, v48 row_ror:8 row_mask:0xf bank_mask:0xf bound_ctrl:1
	v_cndmask_b32_e64 v123, v123, v2, s[24:25]
	ds_read_b128 v[136:139], v124 offset:38016
	ds_read_b128 v[140:143], v124 offset:38272
	ds_read_b128 v[144:147], v124 offset:38528
	ds_read_b128 v[148:151], v124 offset:38784
	ds_read_b128 v[152:155], v124 offset:39040
	ds_read_b32 v156, v110 offset:39296
	v_pk_fma_f32 v[106:107], v[164:165], v[48:49], v[32:33] op_sel_hi:[1,0,1]
	v_pk_fma_f32 v[108:109], v[166:167], v[48:49], v[34:35] op_sel_hi:[1,0,1]
	s_waitcnt lgkmcnt(11)
	v_mul_f32_e32 v125, v188, v106
	v_mul_f32_e32 v32, v176, v106
	v_fmac_f32_e32 v125, v107, v189
	v_fmac_f32_e32 v32, v107, v177
	v_fmac_f32_e32 v125, v108, v190
	v_fmac_f32_e32 v32, v108, v178
	v_fmac_f32_e32 v125, v109, v191
	s_waitcnt lgkmcnt(9)
	v_pk_mul_f32 v[28:29], v[196:197], v[106:107]
	v_pk_mul_f32 v[30:31], v[198:199], v[108:109]
	v_fmac_f32_e32 v32, v109, v179
	s_waitcnt lgkmcnt(6)
	v_pk_fma_f32 v[30:31], v[202:203], v[208:209], v[30:31] op_sel_hi:[1,0,1]
	v_pk_fma_f32 v[28:29], v[200:201], v[208:209], v[28:29] op_sel_hi:[1,0,1]
	v_add_f32_dpp v2, v125, v125 quad_perm:[1,0,3,2] row_mask:0xf bank_mask:0xf bound_ctrl:1
	v_add_f32_dpp v32, v32, v32 quad_perm:[1,0,3,2] row_mask:0xf bank_mask:0xf bound_ctrl:1
	s_nop 0
	v_add_f32_dpp v2, v2, v2 quad_perm:[2,3,0,1] row_mask:0xf bank_mask:0xf bound_ctrl:1
	v_add_f32_dpp v32, v32, v32 quad_perm:[2,3,0,1] row_mask:0xf bank_mask:0xf bound_ctrl:1
	s_nop 0
	v_add_f32_dpp v2, v2, v2 row_ror:4 row_mask:0xf bank_mask:0xf bound_ctrl:1
	v_add_f32_dpp v32, v32, v32 row_ror:4 row_mask:0xf bank_mask:0xf bound_ctrl:1
	s_nop 0
	v_add_f32_dpp v2, v2, v2 row_ror:8 row_mask:0xf bank_mask:0xf bound_ctrl:1
	v_add_f32_dpp v32, v32, v32 row_ror:8 row_mask:0xf bank_mask:0xf bound_ctrl:1
	v_pk_fma_f32 v[106:107], v[192:193], v[2:3], v[28:29] op_sel_hi:[1,0,1]
	v_cndmask_b32_e64 v123, v123, v32, s[26:27]
	ds_read_b128 v[160:163], v124 offset:39424
	ds_read_b128 v[164:167], v124 offset:39680
	ds_read_b128 v[168:171], v124 offset:39936
	ds_read_b128 v[172:175], v124 offset:40192
	ds_read_b128 v[176:179], v124 offset:40448
	ds_read_b32 v158, v110 offset:40704
	v_pk_fma_f32 v[108:109], v[194:195], v[2:3], v[30:31] op_sel_hi:[1,0,1]
	v_mul_f32_e32 v2, v204, v106
	s_waitcnt lgkmcnt(11)
; #define LAS __attribute__((address_space(3)))
; __device__ __forceinline__ float row16_sum(float x) { x += dpp_mov<0xB1>(x); x += dpp_mov<0x4E>(x); x += dpp_mov<0x124>(x); x += dpp_mov<0x128>(x); return x; }
; __device__ __forceinline__ void scan_phase(const KAS Args& a, LAS unsigned char* lds, int i, const int tid_, const int bid, const int nblk) {
;     ...
;                 const LAS float* sb = buf + 4 * cgp; const LAS float* vb = buf + 320 + rl;
;                 f32x4 kk4 = *(const LAS f32x4*)(sb), nb4 = *(const LAS f32x4*)(sb + 64), w4 = *(const LAS f32x4*)(sb + 128), k4 = *(const LAS f32x4*)(sb + 192), r4 = *(const LAS f32x4*)(sb + 256);
;                 float v = vb[0], ysel = 0.f;
; #pragma unroll
;                 for (int t = 0; t < TC; ++t) {
;                     f32x4 kk4n = kk4, nb4n = nb4, w4n = w4, k4n = k4, r4n = r4; float vn = v;
;                     if (t + 1 < TC) { const LAS float* sn = sb + (t + 1) * SST;
;                         kk4n = *(const LAS f32x4*)(sn); nb4n = *(const LAS f32x4*)(sn + 64); w4n = *(const LAS f32x4*)(sn + 128); k4n = *(const LAS f32x4*)(sn + 192); r4n = *(const LAS f32x4*)(sn + 256); vn = vb[(t + 1) * SST]; }
;                     __builtin_amdgcn_sched_barrier(0x6);
;                     float sa = fmaf(S[3], kk4[3], fmaf(S[2], kk4[2], fmaf(S[1], kk4[1], S[0] * kk4[0])));
;                     const f32x4 Tm = S * w4 + k4 * v;
;                     sa = row16_sum(sa);
;                     S = Tm + nb4 * sa;
;                     float y = fmaf(S[3], r4[3], fmaf(S[2], r4[2], fmaf(S[1], r4[1], S[0] * r4[0]))); y = row16_sum(y);
;                     ysel = (cgp == (t & 15)) ? y : ysel;
;                     if ((t & 15) == 15) yb[(t - 15 + cgp) * 32 + rl] = ysel;
;                     kk4 = kk4n; nb4 = nb4n; w4 = w4n; k4 = k4n; r4 = r4n; v = vn; }
	v_mul_f32_e32 v125, v136, v106
	v_fmac_f32_e32 v2, v107, v205
	v_fmac_f32_e32 v125, v107, v137
	v_fmac_f32_e32 v2, v108, v206
	v_fmac_f32_e32 v125, v108, v138
	v_fmac_f32_e32 v2, v109, v207
	v_fmac_f32_e32 v125, v109, v139
	s_waitcnt lgkmcnt(9)
	v_pk_mul_f32 v[32:33], v[144:145], v[106:107]
	v_add_f32_dpp v2, v2, v2 quad_perm:[1,0,3,2] row_mask:0xf bank_mask:0xf bound_ctrl:1
	v_add_f32_dpp v48, v125, v125 quad_perm:[1,0,3,2] row_mask:0xf bank_mask:0xf bound_ctrl:1
	s_waitcnt lgkmcnt(6)
	v_pk_fma_f32 v[32:33], v[148:149], v[156:157], v[32:33] op_sel_hi:[1,0,1]
	v_add_f32_dpp v2, v2, v2 quad_perm:[2,3,0,1] row_mask:0xf bank_mask:0xf bound_ctrl:1
	v_add_f32_dpp v48, v48, v48 quad_perm:[2,3,0,1] row_mask:0xf bank_mask:0xf bound_ctrl:1
	v_pk_mul_f32 v[34:35], v[146:147], v[108:109]
	v_add_f32_dpp v2, v2, v2 row_ror:4 row_mask:0xf bank_mask:0xf bound_ctrl:1
	v_add_f32_dpp v48, v48, v48 row_ror:4 row_mask:0xf bank_mask:0xf bound_ctrl:1
	v_pk_fma_f32 v[34:35], v[150:151], v[156:157], v[34:35] op_sel_hi:[1,0,1]
	v_add_f32_dpp v2, v2, v2 row_ror:8 row_mask:0xf bank_mask:0xf bound_ctrl:1
	v_add_f32_dpp v48, v48, v48 row_ror:8 row_mask:0xf bank_mask:0xf bound_ctrl:1
	v_cndmask_b32_e64 v123, v123, v2, s[28:29]
	ds_read_b128 v[188:191], v124 offset:40832
	ds_read_b128 v[192:195], v124 offset:41088
	ds_read_b128 v[196:199], v124 offset:41344
	ds_read_b128 v[200:203], v124 offset:41600
	ds_read_b128 v[204:207], v124 offset:41856
	ds_read_b32 v208, v110 offset:42112
	v_pk_fma_f32 v[40:41], v[140:141], v[48:49], v[32:33] op_sel_hi:[1,0,1]
	v_pk_fma_f32 v[42:43], v[142:143], v[48:49], v[34:35] op_sel_hi:[1,0,1]
	v_mul_f32_e32 v32, v152, v40
	s_waitcnt lgkmcnt(11)
	v_mul_f32_e32 v61, v160, v40
	v_fmac_f32_e32 v32, v41, v153
	v_fmac_f32_e32 v61, v41, v161
	v_fmac_f32_e32 v32, v42, v154
	v_fmac_f32_e32 v61, v42, v162
	v_fmac_f32_e32 v32, v43, v155
	v_fmac_f32_e32 v61, v43, v163
	s_waitcnt lgkmcnt(9)
	v_pk_mul_f32 v[28:29], v[168:169], v[40:41]
	v_pk_mul_f32 v[30:31], v[170:171], v[42:43]
	v_add_f32_dpp v32, v32, v32 quad_perm:[1,0,3,2] row_mask:0xf bank_mask:0xf bound_ctrl:1
	s_waitcnt lgkmcnt(6)
	v_pk_fma_f32 v[30:31], v[174:175], v[158:159], v[30:31] op_sel_hi:[1,0,1]
	v_pk_fma_f32 v[28:29], v[172:173], v[158:159], v[28:29] op_sel_hi:[1,0,1]
	v_add_f32_dpp v2, v61, v61 quad_perm:[1,0,3,2] row_mask:0xf bank_mask:0xf bound_ctrl:1
	v_add_f32_dpp v32, v32, v32 quad_perm:[2,3,0,1] row_mask:0xf bank_mask:0xf bound_ctrl:1
	s_nop 0
	v_add_f32_dpp v2, v2, v2 quad_perm:[2,3,0,1] row_mask:0xf bank_mask:0xf bound_ctrl:1
	v_add_f32_dpp v32, v32, v32 row_ror:4 row_mask:0xf bank_mask:0xf bound_ctrl:1
	s_nop 0
	v_add_f32_dpp v2, v2, v2 row_ror:4 row_mask:0xf bank_mask:0xf bound_ctrl:1
	v_add_f32_dpp v32, v32, v32 row_ror:8 row_mask:0xf bank_mask:0xf bound_ctrl:1
	v_cndmask_b32_e64 v60, v123, v32, s[30:31]
	v_add_f32_dpp v2, v2, v2 row_ror:8 row_mask:0xf bank_mask:0xf bound_ctrl:1
	ds_read_b128 v[136:139], v124 offset:42240
	ds_read_b128 v[140:143], v124 offset:42496
	ds_read_b128 v[144:147], v124 offset:42752
	ds_read_b128 v[148:151], v124 offset:43008
	ds_read_b128 v[152:155], v124 offset:43264
	ds_read_b32 v156, v110 offset:43520
	v_pk_fma_f32 v[28:29], v[164:165], v[2:3], v[28:29] op_sel_hi:[1,0,1]
	v_pk_fma_f32 v[30:31], v[166:167], v[2:3], v[30:31] op_sel_hi:[1,0,1]
	v_mul_f32_e32 v2, v176, v28
	s_waitcnt lgkmcnt(11)
	v_mul_f32_e32 v32, v188, v28
	v_fmac_f32_e32 v2, v29, v177
	v_fmac_f32_e32 v32, v29, v189
	v_fmac_f32_e32 v2, v30, v178
	v_fmac_f32_e32 v32, v30, v190
	v_fmac_f32_e32 v2, v31, v179
	v_fmac_f32_e32 v32, v31, v191
	s_waitcnt lgkmcnt(9)
	v_pk_mul_f32 v[28:29], v[196:197], v[28:29]
	v_add_f32_dpp v2, v2, v2 quad_perm:[1,0,3,2] row_mask:0xf bank_mask:0xf bound_ctrl:1
	v_add_f32_dpp v32, v32, v32 quad_perm:[1,0,3,2] row_mask:0xf bank_mask:0xf bound_ctrl:1
	s_waitcnt lgkmcnt(6)
	v_pk_fma_f32 v[28:29], v[200:201], v[208:209], v[28:29] op_sel_hi:[1,0,1]
	v_add_f32_dpp v2, v2, v2 quad_perm:[2,3,0,1] row_mask:0xf bank_mask:0xf bound_ctrl:1
	v_add_f32_dpp v32, v32, v32 quad_perm:[2,3,0,1] row_mask:0xf bank_mask:0xf bound_ctrl:1
	v_pk_mul_f32 v[30:31], v[198:199], v[30:31]
	v_add_f32_dpp v2, v2, v2 row_ror:4 row_mask:0xf bank_mask:0xf bound_ctrl:1
	v_add_f32_dpp v32, v32, v32 row_ror:4 row_mask:0xf bank_mask:0xf bound_ctrl:1
	v_pk_fma_f32 v[30:31], v[202:203], v[208:209], v[30:31] op_sel_hi:[1,0,1]
	v_add_f32_dpp v2, v2, v2 row_ror:8 row_mask:0xf bank_mask:0xf bound_ctrl:1
	v_add_f32_dpp v32, v32, v32 row_ror:8 row_mask:0xf bank_mask:0xf bound_ctrl:1
	v_cndmask_b32_e64 v44, v60, v2, s[34:35]
	ds_read_b128 v[160:163], v124 offset:43648
	ds_read_b128 v[164:167], v124 offset:43904
	ds_read_b128 v[168:171], v124 offset:44160
	ds_read_b128 v[172:175], v124 offset:44416
	ds_read_b128 v[176:179], v124 offset:44672
	ds_read_b32 v158, v110 offset:44928
	v_pk_fma_f32 v[108:109], v[192:193], v[32:33], v[28:29] op_sel_hi:[1,0,1]
	v_pk_fma_f32 v[106:107], v[194:195], v[32:33], v[30:31] op_sel_hi:[1,0,1]
	s_waitcnt lgkmcnt(11)
	v_mul_f32_e32 v64, v136, v108
	v_fmac_f32_e32 v64, v109, v137
	v_fmac_f32_e32 v64, v106, v138
	v_fmac_f32_e32 v64, v107, v139
	s_waitcnt lgkmcnt(9)
	v_pk_mul_f32 v[60:61], v[144:145], v[108:109]
	v_pk_mul_f32 v[62:63], v[146:147], v[106:107]
	s_waitcnt lgkmcnt(6)
; __device__ __forceinline__ float row16_sum(float x) { x += dpp_mov<0xB1>(x); x += dpp_mov<0x4E>(x); x += dpp_mov<0x124>(x); x += dpp_mov<0x128>(x); return x; }
; __device__ __forceinline__ void up4(const u32x2 w, float (&f)[4]) { f[0] = bflo(w.x); f[1] = bfhi(w.x); f[2] = bflo(w.y); f[3] = bfhi(w.y); }
; __device__ __forceinline__ void scan_stage(const u32x2 (&pz)[8], LAS float* buf, float* RKB, size_t mrow0, int t0, int tid, int h, int half, ...
;     ...
;     up4(pz[0], zr); up4(pz[1], zk); up4(pz[2], zv); up4(pz[3], zrp); up4(pz[4], zkp); up4(pz[5], zvp); up4(pz[6], ew); up4(pz[7], ic);
;     f32x4 r, k2, v, kkv, w; float n2 = 0.f, rkb = 0.f;
; #pragma unroll
;     for (int e = 0; e < 4; ++e) { r[e] = zr[e] + (zrp[e] - zr[e]) * mu_r[e]; const float k = zk[e] + (zkp[e] - zk[e]) * mu_k[e]; v[e] = zv[e] + (zvp[e] - zv[e]) * mu_v[e];
;         kkv[e] = k * kkc[e]; n2 += kkv[e] * kkv[e]; k2[e] = k * (1.0f + (ic[e] - 1.0f) * kac[e]); w[e] = __builtin_amdgcn_exp2f(-1.4426950408889634f * ew[e]); rkb += r[e] * k2[e] * rkc[e]; }
;     n2 = row16_sum(n2); rkb = row16_sum(rkb);
;     const float inv = __builtin_amdgcn_rsqf(fmaxf(n2, 1e-24f));
;     const f32x4 kkn = kkv * inv; f32x4 nb;
; #pragma unroll
;     for (int e = 0; e < 4; ++e) nb[e] = -kkn[e] * ic[e];
;     if (half == 0 && cgp == 0) RKB[(mrow0 + t0 + tl) * 8 + h] = rkb;
; __device__ __forceinline__ void scan_phase(const KAS Args& a, LAS unsigned char* lds, int i, const int tid_, const int bid, const int nblk) {
;     ...
;                     float sa = fmaf(S[3], kk4[3], fmaf(S[2], kk4[2], fmaf(S[1], kk4[1], S[0] * kk4[0])));
;                     const f32x4 Tm = S * w4 + k4 * v;
;                     sa = row16_sum(sa);
;                     S = Tm + nb4 * sa;
;                     float y = fmaf(S[3], r4[3], fmaf(S[2], r4[2], fmaf(S[1], r4[1], S[0] * r4[0]))); y = row16_sum(y);
;                     ysel = (cgp == (t & 15)) ? y : ysel;
;                     if ((t & 15) == 15) yb[(t - 15 + cgp) * 32 + rl] = ysel;
;                     kk4 = kk4n; nb4 = nb4n; w4 = w4n; k4 = k4n; r4 = r4n; v = vn; }
	v_pk_fma_f32 v[56:57], v[148:149], v[156:157], v[60:61] op_sel_hi:[1,0,1]
	v_pk_fma_f32 v[58:59], v[150:151], v[156:157], v[62:63] op_sel_hi:[1,0,1]
	v_add_f32_dpp v2, v64, v64 quad_perm:[1,0,3,2] row_mask:0xf bank_mask:0xf bound_ctrl:1
	v_mul_f32_e32 v28, v204, v108
	v_fmac_f32_e32 v28, v109, v205
	v_add_f32_dpp v2, v2, v2 quad_perm:[2,3,0,1] row_mask:0xf bank_mask:0xf bound_ctrl:1
	v_fmac_f32_e32 v28, v106, v206
	v_fmac_f32_e32 v28, v107, v207
	v_add_f32_dpp v2, v2, v2 row_ror:4 row_mask:0xf bank_mask:0xf bound_ctrl:1
	s_nop 0
	v_add_f32_dpp v28, v28, v28 quad_perm:[1,0,3,2] row_mask:0xf bank_mask:0xf bound_ctrl:1
	v_add_f32_dpp v2, v2, v2 row_ror:8 row_mask:0xf bank_mask:0xf bound_ctrl:1
	v_pk_fma_f32 v[40:41], v[140:141], v[2:3], v[56:57] op_sel_hi:[1,0,1]
	v_pk_fma_f32 v[42:43], v[142:143], v[2:3], v[58:59] op_sel_hi:[1,0,1]
	v_mul_f32_e32 v2, v152, v40
	v_fmac_f32_e32 v2, v41, v153
	v_fmac_f32_e32 v2, v42, v154
	v_fmac_f32_e32 v2, v43, v155
	v_add_f32_dpp v28, v28, v28 quad_perm:[2,3,0,1] row_mask:0xf bank_mask:0xf bound_ctrl:1
	s_nop 0
	v_add_f32_dpp v2, v2, v2 quad_perm:[1,0,3,2] row_mask:0xf bank_mask:0xf bound_ctrl:1
	v_add_f32_dpp v28, v28, v28 row_ror:4 row_mask:0xf bank_mask:0xf bound_ctrl:1
	s_nop 0
	v_add_f32_dpp v2, v2, v2 quad_perm:[2,3,0,1] row_mask:0xf bank_mask:0xf bound_ctrl:1
	v_add_f32_dpp v28, v28, v28 row_ror:8 row_mask:0xf bank_mask:0xf bound_ctrl:1
	v_cndmask_b32_e64 v123, v44, v28, s[36:37]
	v_add_f32_dpp v2, v2, v2 row_ror:4 row_mask:0xf bank_mask:0xf bound_ctrl:1
	s_nop 1
	v_add_f32_dpp v2, v2, v2 row_ror:8 row_mask:0xf bank_mask:0xf bound_ctrl:1
	v_cndmask_b32_e64 v56, v123, v2, s[38:39]
	s_waitcnt lgkmcnt(5)
	v_mul_f32_e32 v2, v160, v40
	v_fmac_f32_e32 v2, v41, v161
	v_fmac_f32_e32 v2, v42, v162
	v_fmac_f32_e32 v2, v43, v163
	s_waitcnt lgkmcnt(3)
	v_pk_mul_f32 v[36:37], v[168:169], v[40:41]
	v_pk_mul_f32 v[38:39], v[170:171], v[42:43]
	v_add_f32_dpp v2, v2, v2 quad_perm:[1,0,3,2] row_mask:0xf bank_mask:0xf bound_ctrl:1
	s_waitcnt lgkmcnt(0)
	v_pk_fma_f32 v[36:37], v[172:173], v[158:159], v[36:37] op_sel_hi:[1,0,1]
	v_pk_fma_f32 v[38:39], v[174:175], v[158:159], v[38:39] op_sel_hi:[1,0,1]
	v_add_f32_dpp v2, v2, v2 quad_perm:[2,3,0,1] row_mask:0xf bank_mask:0xf bound_ctrl:1
	s_nop 1
	v_add_f32_dpp v2, v2, v2 row_ror:4 row_mask:0xf bank_mask:0xf bound_ctrl:1
	s_nop 1
	v_add_f32_dpp v2, v2, v2 row_ror:8 row_mask:0xf bank_mask:0xf bound_ctrl:1
	v_pk_fma_f32 v[36:37], v[164:165], v[2:3], v[36:37] op_sel_hi:[1,0,1]
	v_pk_fma_f32 v[38:39], v[166:167], v[2:3], v[38:39] op_sel_hi:[1,0,1]
	v_mul_f32_e32 v2, v176, v36
	v_fmac_f32_e32 v2, v37, v177
	v_fmac_f32_e32 v2, v38, v178
	v_fmac_f32_e32 v2, v39, v179
	s_nop 1
	v_add_f32_dpp v2, v2, v2 quad_perm:[1,0,3,2] row_mask:0xf bank_mask:0xf bound_ctrl:1
	s_nop 1
	v_add_f32_dpp v2, v2, v2 quad_perm:[2,3,0,1] row_mask:0xf bank_mask:0xf bound_ctrl:1
	s_nop 1
	v_add_f32_dpp v2, v2, v2 row_ror:4 row_mask:0xf bank_mask:0xf bound_ctrl:1
	s_nop 1
	v_add_f32_dpp v2, v2, v2 row_ror:8 row_mask:0xf bank_mask:0xf bound_ctrl:1
	v_cndmask_b32_e64 v2, v56, v2, s[40:41]
	ds_write_b32 v122, v2 offset:2048
	s_cbranch_vccnz .LBB0_183
	s_waitcnt vmcnt(4)
	v_lshlrev_b32_e32 v28, 16, v80
	v_and_b32_e32 v29, 0xffff0000, v80
	v_lshlrev_b32_e32 v30, 16, v86
	v_and_b32_e32 v31, 0xffff0000, v86
	v_pk_add_f32 v[30:31], v[30:31], v[28:29] neg_lo:[0,1] neg_hi:[0,1]
	s_waitcnt vmcnt(3)
	v_lshlrev_b32_e32 v32, 16, v88
	v_pk_fma_f32 v[28:29], v[16:17], v[30:31], v[28:29]
	v_lshlrev_b32_e32 v30, 16, v82
	v_and_b32_e32 v31, 0xffff0000, v82
	v_and_b32_e32 v33, 0xffff0000, v88
	s_waitcnt vmcnt(0)
	v_lshlrev_b32_e32 v40, 16, v94
	v_and_b32_e32 v41, 0xffff0000, v94
	v_pk_add_f32 v[32:33], v[32:33], v[30:31] neg_lo:[0,1] neg_hi:[0,1]
	v_lshlrev_b32_e32 v46, 16, v89
	v_pk_fma_f32 v[30:31], v[20:21], v[32:33], v[30:31]
	v_pk_add_f32 v[32:33], v[40:41], -1.0 op_sel_hi:[1,0]
	v_pk_mul_f32 v[42:43], v[12:13], v[30:31]
	v_pk_fma_f32 v[32:33], v[24:25], v[32:33], 1.0 op_sel_hi:[1,1,0]
	v_and_b32_e32 v47, 0xffff0000, v89
	v_pk_mul_f32 v[32:33], v[30:31], v[32:33]
	v_lshlrev_b32_e32 v30, 16, v81
	v_pk_mul_f32 v[34:35], v[28:29], v[32:33]
	v_and_b32_e32 v31, 0xffff0000, v81
	v_fma_f32 v54, v4, v34, 0
	v_fmac_f32_e32 v54, v5, v35
	v_lshlrev_b32_e32 v34, 16, v87
	v_and_b32_e32 v35, 0xffff0000, v87
	v_pk_add_f32 v[34:35], v[34:35], v[30:31] neg_lo:[0,1] neg_hi:[0,1]
	v_lshlrev_b32_e32 v44, 16, v95
	v_pk_fma_f32 v[30:31], v[18:19], v[34:35], v[30:31]
	v_lshlrev_b32_e32 v34, 16, v83
	v_and_b32_e32 v35, 0xffff0000, v83
	v_and_b32_e32 v45, 0xffff0000, v95
	v_pk_add_f32 v[46:47], v[46:47], v[34:35] neg_lo:[0,1] neg_hi:[0,1]
	v_pk_mul_f32 v[48:49], v[42:43], v[42:43]
	v_pk_fma_f32 v[46:47], v[22:23], v[46:47], v[34:35]
	v_pk_add_f32 v[34:35], v[44:45], -1.0 op_sel_hi:[1,0]
	v_add_f32_e32 v2, v48, v49
	v_pk_fma_f32 v[34:35], v[26:27], v[34:35], 1.0 op_sel_hi:[1,1,0]
	v_mov_b32_e32 v48, 0
	v_pk_mul_f32 v[34:35], v[46:47], v[34:35]
	v_pk_mul_f32 v[46:47], v[14:15], v[46:47]
	v_pk_mul_f32 v[50:51], v[30:31], v[34:35]
	v_pk_mul_f32 v[52:53], v[46:47], v[46:47]
	v_fmac_f32_e32 v54, v6, v50
	v_add_f32_e32 v2, v52, v2
	v_add_f32_e32 v2, v53, v2
	v_fmac_f32_e32 v54, v7, v51
	v_mov_b32_e32 v50, 0
	v_add_f32_dpp v2, v2, v2 quad_perm:[1,0,3,2] row_mask:0xf bank_mask:0xf bound_ctrl:1
	v_add_f32_dpp v49, v54, v54 quad_perm:[1,0,3,2] row_mask:0xf bank_mask:0xf bound_ctrl:1
	s_nop 0
	v_add_f32_dpp v2, v2, v2 quad_perm:[2,3,0,1] row_mask:0xf bank_mask:0xf bound_ctrl:1
	v_add_f32_dpp v49, v49, v49 quad_perm:[2,3,0,1] row_mask:0xf bank_mask:0xf bound_ctrl:1
	s_nop 0
	v_add_f32_dpp v2, v2, v2 row_ror:4 row_mask:0xf bank_mask:0xf bound_ctrl:1
	v_add_f32_dpp v49, v49, v49 row_ror:4 row_mask:0xf bank_mask:0xf bound_ctrl:1
	s_nop 0
	v_mov_b32_dpp v48, v2 row_ror:8 row_mask:0xf bank_mask:0xf
	v_mov_b32_dpp v50, v49 row_ror:8 row_mask:0xf bank_mask:0xf
	s_and_saveexec_b64 s[2:3], s[42:43]
	s_cbranch_execz .LBB0_193
	v_lshl_add_u64 v[52:53], s[88:89], 0, v[100:101]
	v_add_f32_e32 v49, v49, v50
	global_store_dword v[52:53], v49, off
